# P8 K loop: per-MFMA-block s_setprio toggles removed, one static raise of the trailing wave half per unit
# speedup vs baseline: 1.0043x; 1.0043x over previous
; #define PG8_STAGE(bufoff, gbase, voff) do { _Pragma("unroll") for (int _i = 0; _i < 2; ++_i) \
;         __builtin_amdgcn_global_load_lds((const unsigned*)((const char*)(gbase) + (voff)[_i]), (PG8_LAS unsigned*)(lds + (bufoff) + ldsw + _i * 8192), 16, 0, 0); } while (0)
; #define PG8_LDA(dst, b, h) do { _Pragma("unroll") for (int m = 0; m < 4; ++m) _Pragma("unroll") for (int k = 0; k < 2; ++k) dst[m][k] = *(const PG8_LAS bf16x8*)(lds + PG8_SA(b, h) + aoff + m * 2048 + k * 1024); } while (0)
; #define PG8_LDB(dst, b, h) do { _Pragma("unroll") for (int n = 0; n < 2; ++n) _Pragma("unroll") for (int k = 0; k < 2; ++k) dst[n][k] = *(const PG8_LAS bf16x8*)(lds + PG8_SB(b, h) + boff + n * 2048 + k * 1024); } while (0)
; #define PG8_WAIT_V(n) asm volatile("s_waitcnt vmcnt(" #n ")" ::: "memory")
; #define PG8_WAIT_L(n) asm volatile("s_waitcnt lgkmcnt(" #n ")" ::: "memory")
; #define PG8_BAR __builtin_amdgcn_s_barrier()
; #define PG8_SCHED __builtin_amdgcn_sched_barrier(0)
; template <class Epi, class Sched, bool ALIGN_EPI = false, bool SP2 = false>
; __device__ __forceinline__ void gemm_phase(PG8_LAS unsigned char* lds, const Gemm g, const Sched& S, const Epi& E) {
;     ...
;             PG8_LDB(B0, 0, 0); PG8_LDB(B1, 0, 1); PG8_SCHED; PG8_LDA(At, 0, 0); PG8_STAGE(PG8_SA(1, 1), a1 + hstep, voffA);
;             PG8_WAIT_V(8); PG8_WAIT_L(0); PG8_BAR; PG8_MMA(0, 0, At, B0); PG8_MMA(0, 1, At, B1); PG8_BAR; PG8_SCHED;
;             PG8_LDA(At, 0, 1); PG8_STAGE(PG8_SB(0, 0), b2, voffB); PG8_STAGE(PG8_SB(0, 1), b2 + hstep, voffB); PG8_STAGE(PG8_SA(0, 0), a2, voffA);
;             PG8_WAIT_V(8); PG8_WAIT_L(0); PG8_BAR; PG8_MMA(1, 0, At, B0); PG8_MMA(1, 1, At, B1); PG8_BAR; PG8_SCHED;
.LBB0_886:
	ds_read_b128 v[140:143], v178
	ds_read_b128 v[144:147], v178 offset:1024
	ds_read_b128 v[148:151], v178 offset:2048
	ds_read_b128 v[152:155], v178 offset:3072
	ds_read_b128 v[156:159], v179
	ds_read_b128 v[160:163], v179 offset:1024
	ds_read_b128 v[164:167], v179 offset:2048
	ds_read_b128 v[168:171], v179 offset:3072
	s_add_u32 s26, s76, 0xfffc0080
	s_addc_u32 s27, s77, -1
	s_cmp_eq_u32 vcc_hi, 12
	s_cselect_b32 s81, s17, s27
	s_cselect_b32 s80, s19, s26
	s_cselect_b32 s79, s67, vcc_lo
	s_cselect_b32 s78, s69, s75
	v_lshl_add_u64 v[216:217], s[76:77], 0, v[132:133]
	s_add_i32 m0, s92, 0xc000
	ds_read_b128 v[182:185], v180
	ds_read_b128 v[186:189], v180 offset:1024
	ds_read_b128 v[190:193], v180 offset:2048
	ds_read_b128 v[196:199], v180 offset:3072
	ds_read_b128 v[200:203], v180 offset:4096
	ds_read_b128 v[204:207], v180 offset:5120
	ds_read_b128 v[208:211], v180 offset:6144
	ds_read_b128 v[212:215], v180 offset:7168
	global_load_lds_dwordx4 v[216:217], off
	v_lshl_add_u64 v[216:217], s[76:77], 0, v[134:135]
	s_add_i32 m0, s92, 0xe000
	s_nop 0
	global_load_lds_dwordx4 v[216:217], off
	s_waitcnt vmcnt(8)
	s_waitcnt lgkmcnt(0)
	s_barrier
	s_waitcnt lgkmcnt(0)
	v_mfma_f32_16x16x32_bf16 v[124:127], v[182:185], v[140:143], v[124:127]
	v_mfma_f32_16x16x32_bf16 v[116:119], v[182:185], v[148:151], v[116:119]
	v_mfma_f32_16x16x32_bf16 v[108:111], v[190:193], v[140:143], v[108:111]
	v_mfma_f32_16x16x32_bf16 v[100:103], v[190:193], v[148:151], v[100:103]
	v_mfma_f32_16x16x32_bf16 v[92:95], v[200:203], v[140:143], v[92:95]
	v_mfma_f32_16x16x32_bf16 v[84:87], v[200:203], v[148:151], v[84:87]
	v_mfma_f32_16x16x32_bf16 v[68:71], v[208:211], v[140:143], v[68:71]
	v_mfma_f32_16x16x32_bf16 v[76:79], v[208:211], v[148:151], v[76:79]
	v_mfma_f32_16x16x32_bf16 v[124:127], v[186:189], v[144:147], v[124:127]
	v_mfma_f32_16x16x32_bf16 v[116:119], v[186:189], v[152:155], v[116:119]
	v_mfma_f32_16x16x32_bf16 v[108:111], v[196:199], v[144:147], v[108:111]
	v_mfma_f32_16x16x32_bf16 v[100:103], v[196:199], v[152:155], v[100:103]
	v_mfma_f32_16x16x32_bf16 v[92:95], v[204:207], v[144:147], v[92:95]
	v_mfma_f32_16x16x32_bf16 v[84:87], v[204:207], v[152:155], v[84:87]
	v_mfma_f32_16x16x32_bf16 v[68:71], v[212:215], v[144:147], v[68:71]
	v_mfma_f32_16x16x32_bf16 v[76:79], v[212:215], v[152:155], v[76:79]
	v_mfma_f32_16x16x32_bf16 v[120:123], v[182:185], v[156:159], v[120:123]
	v_mfma_f32_16x16x32_bf16 v[112:115], v[182:185], v[164:167], v[112:115]
	v_mfma_f32_16x16x32_bf16 v[104:107], v[190:193], v[156:159], v[104:107]
	v_mfma_f32_16x16x32_bf16 v[96:99], v[190:193], v[164:167], v[96:99]
	v_mfma_f32_16x16x32_bf16 v[88:91], v[200:203], v[156:159], v[88:91]
	v_mfma_f32_16x16x32_bf16 v[80:83], v[200:203], v[164:167], v[80:83]
	v_mfma_f32_16x16x32_bf16 v[64:67], v[208:211], v[156:159], v[64:67]
	v_mfma_f32_16x16x32_bf16 v[72:75], v[208:211], v[164:167], v[72:75]
	v_mfma_f32_16x16x32_bf16 v[120:123], v[186:189], v[160:163], v[120:123]
	v_mfma_f32_16x16x32_bf16 v[112:115], v[186:189], v[168:171], v[112:115]
	v_mfma_f32_16x16x32_bf16 v[104:107], v[196:199], v[160:163], v[104:107]
	v_mfma_f32_16x16x32_bf16 v[96:99], v[196:199], v[168:171], v[96:99]
	v_mfma_f32_16x16x32_bf16 v[88:91], v[204:207], v[160:163], v[88:91]
	v_mfma_f32_16x16x32_bf16 v[80:83], v[204:207], v[168:171], v[80:83]
	v_mfma_f32_16x16x32_bf16 v[64:67], v[212:215], v[160:163], v[64:67]
	v_mfma_f32_16x16x32_bf16 v[72:75], v[212:215], v[168:171], v[72:75]
	s_barrier
	s_add_i32 s26, s33, s91
	v_lshl_add_u64 v[216:217], s[78:79], 0, v[128:129]
	s_mov_b32 m0, s26
	ds_read_b128 v[182:185], v180 offset:16384
	ds_read_b128 v[186:189], v180 offset:17408
	ds_read_b128 v[190:193], v180 offset:18432
	ds_read_b128 v[196:199], v180 offset:19456
	ds_read_b128 v[200:203], v180 offset:20480
	ds_read_b128 v[204:207], v180 offset:21504
	ds_read_b128 v[208:211], v180 offset:22528
	ds_read_b128 v[212:215], v180 offset:23552
	global_load_lds_dwordx4 v[216:217], off
	s_add_i32 m0, s26, 0x2000
	s_add_u32 s26, s78, 0x40000
	v_lshl_add_u64 v[218:219], s[78:79], 0, v[130:131]
	s_addc_u32 s27, s79, 0
	s_add_i32 s82, s36, s91
	global_load_lds_dwordx4 v[218:219], off
	v_lshl_add_u64 v[220:221], s[26:27], 0, v[128:129]
	s_mov_b32 m0, s82
	v_lshl_add_u64 v[222:223], s[80:81], 0, v[130:131]
	global_load_lds_dwordx4 v[220:221], off
	v_lshl_add_u64 v[220:221], s[26:27], 0, v[130:131]
	s_add_i32 m0, s82, 0x2000
	s_nop 0
	global_load_lds_dwordx4 v[220:221], off
	v_lshl_add_u64 v[220:221], s[80:81], 0, v[128:129]
	s_mov_b32 m0, s92
	s_nop 0
	global_load_lds_dwordx4 v[220:221], off
	s_mov_b32 m0, s93
	s_nop 0
	global_load_lds_dwordx4 v[222:223], off
	s_waitcnt vmcnt(8)
	s_waitcnt lgkmcnt(0)
	s_barrier
; #define PG8_STAGE(bufoff, gbase, voff) do { _Pragma("unroll") for (int _i = 0; _i < 2; ++_i) \
;         __builtin_amdgcn_global_load_lds((const unsigned*)((const char*)(gbase) + (voff)[_i]), (PG8_LAS unsigned*)(lds + (bufoff) + ldsw + _i * 8192), 16, 0, 0); } while (0)
; #define PG8_LDA(dst, b, h) do { _Pragma("unroll") for (int m = 0; m < 4; ++m) _Pragma("unroll") for (int k = 0; k < 2; ++k) dst[m][k] = *(const PG8_LAS bf16x8*)(lds + PG8_SA(b, h) + aoff + m * 2048 + k * 1024); } while (0)
; #define PG8_LDB(dst, b, h) do { _Pragma("unroll") for (int n = 0; n < 2; ++n) _Pragma("unroll") for (int k = 0; k < 2; ++k) dst[n][k] = *(const PG8_LAS bf16x8*)(lds + PG8_SB(b, h) + boff + n * 2048 + k * 1024); } while (0)
; #define PG8_WAIT_V(n) asm volatile("s_waitcnt vmcnt(" #n ")" ::: "memory")
; #define PG8_WAIT_L(n) asm volatile("s_waitcnt lgkmcnt(" #n ")" ::: "memory")
; #define PG8_BAR __builtin_amdgcn_s_barrier()
; #define PG8_SCHED __builtin_amdgcn_sched_barrier(0)
; template <class Epi, class Sched, bool ALIGN_EPI = false, bool SP2 = false>
; __device__ __forceinline__ void gemm_phase(PG8_LAS unsigned char* lds, const Gemm g, const Sched& S, const Epi& E) {
;     ...
;             PG8_WAIT_V(8); PG8_WAIT_L(0); PG8_BAR; PG8_MMA(1, 0, At, B0); PG8_MMA(1, 1, At, B1); PG8_BAR; PG8_SCHED;
;             PG8_LDB(B0, 1, 0); PG8_LDB(B1, 1, 1); PG8_SCHED; PG8_LDA(At, 1, 0); PG8_STAGE(PG8_SA(0, 1), a2 + hstep, voffA);
;             PG8_WAIT_V(8); PG8_WAIT_L(0); PG8_BAR; PG8_MMA(0, 0, At, B0); PG8_MMA(0, 1, At, B1); PG8_BAR; PG8_SCHED;
	s_waitcnt lgkmcnt(0)
	v_mfma_f32_16x16x32_bf16 v[60:63], v[182:185], v[140:143], v[60:63]
	v_mfma_f32_16x16x32_bf16 v[52:55], v[182:185], v[148:151], v[52:55]
	v_mfma_f32_16x16x32_bf16 v[44:47], v[190:193], v[140:143], v[44:47]
	v_mfma_f32_16x16x32_bf16 v[36:39], v[190:193], v[148:151], v[36:39]
	v_mfma_f32_16x16x32_bf16 v[28:31], v[200:203], v[140:143], v[28:31]
	v_mfma_f32_16x16x32_bf16 v[20:23], v[200:203], v[148:151], v[20:23]
	v_mfma_f32_16x16x32_bf16 v[0:3], v[208:211], v[140:143], v[0:3]
	v_mfma_f32_16x16x32_bf16 v[12:15], v[208:211], v[148:151], v[12:15]
	v_mfma_f32_16x16x32_bf16 v[60:63], v[186:189], v[144:147], v[60:63]
	v_mfma_f32_16x16x32_bf16 v[52:55], v[186:189], v[152:155], v[52:55]
	v_mfma_f32_16x16x32_bf16 v[44:47], v[196:199], v[144:147], v[44:47]
	v_mfma_f32_16x16x32_bf16 v[36:39], v[196:199], v[152:155], v[36:39]
	v_mfma_f32_16x16x32_bf16 v[28:31], v[204:207], v[144:147], v[28:31]
	v_mfma_f32_16x16x32_bf16 v[20:23], v[204:207], v[152:155], v[20:23]
	v_mfma_f32_16x16x32_bf16 v[0:3], v[212:215], v[144:147], v[0:3]
	v_mfma_f32_16x16x32_bf16 v[12:15], v[212:215], v[152:155], v[12:15]
	v_mfma_f32_16x16x32_bf16 v[56:59], v[182:185], v[156:159], v[56:59]
	v_mfma_f32_16x16x32_bf16 v[48:51], v[182:185], v[164:167], v[48:51]
	v_mfma_f32_16x16x32_bf16 v[40:43], v[190:193], v[156:159], v[40:43]
	v_mfma_f32_16x16x32_bf16 v[32:35], v[190:193], v[164:167], v[32:35]
	v_mfma_f32_16x16x32_bf16 v[24:27], v[200:203], v[156:159], v[24:27]
	v_mfma_f32_16x16x32_bf16 v[16:19], v[200:203], v[164:167], v[16:19]
	v_mfma_f32_16x16x32_bf16 v[4:7], v[208:211], v[156:159], v[4:7]
	v_mfma_f32_16x16x32_bf16 v[8:11], v[208:211], v[164:167], v[8:11]
	v_mfma_f32_16x16x32_bf16 v[56:59], v[186:189], v[160:163], v[56:59]
	v_mfma_f32_16x16x32_bf16 v[48:51], v[186:189], v[168:171], v[48:51]
	v_mfma_f32_16x16x32_bf16 v[40:43], v[196:199], v[160:163], v[40:43]
	v_mfma_f32_16x16x32_bf16 v[32:35], v[196:199], v[168:171], v[32:35]
	v_mfma_f32_16x16x32_bf16 v[24:27], v[204:207], v[160:163], v[24:27]
	v_mfma_f32_16x16x32_bf16 v[16:19], v[204:207], v[168:171], v[16:19]
	v_mfma_f32_16x16x32_bf16 v[4:7], v[212:215], v[160:163], v[4:7]
	v_mfma_f32_16x16x32_bf16 v[8:11], v[212:215], v[168:171], v[8:11]
	s_barrier
	s_add_i32 s82, 0, 0x18000
	s_add_i32 s24, 0, 0x1c000
	v_add_u32_e32 v152, s82, v173
	v_add_u32_e32 v168, s24, v173
	ds_read_b128 v[140:143], v152
	ds_read_b128 v[144:147], v152 offset:1024
	ds_read_b128 v[148:151], v152 offset:2048
	ds_read_b128 v[152:155], v152 offset:3072
	ds_read_b128 v[156:159], v168
	ds_read_b128 v[160:163], v168 offset:1024
	ds_read_b128 v[164:167], v168 offset:2048
	ds_read_b128 v[168:171], v168 offset:3072
	s_add_u32 s26, s80, 0x40000
	s_addc_u32 s27, s81, 0
	s_mov_b32 m0, s94
	v_lshl_add_u64 v[224:225], s[26:27], 0, v[128:129]
	ds_read_b128 v[182:185], v180 offset:32768
	ds_read_b128 v[186:189], v180 offset:33792
	ds_read_b128 v[190:193], v180 offset:34816
	ds_read_b128 v[196:199], v180 offset:35840
	ds_read_b128 v[200:203], v180 offset:36864
	ds_read_b128 v[204:207], v180 offset:37888
	ds_read_b128 v[208:211], v180 offset:38912
	ds_read_b128 v[212:215], v180 offset:39936
	global_load_lds_dwordx4 v[224:225], off
	v_lshl_add_u64 v[224:225], s[26:27], 0, v[130:131]
	s_mov_b32 m0, s95
	s_nop 0
	global_load_lds_dwordx4 v[224:225], off
	s_waitcnt vmcnt(8)
	s_waitcnt lgkmcnt(0)
	s_barrier
	s_waitcnt lgkmcnt(0)
	v_mfma_f32_16x16x32_bf16 v[124:127], v[182:185], v[140:143], v[124:127]
	v_mfma_f32_16x16x32_bf16 v[116:119], v[182:185], v[148:151], v[116:119]
	v_mfma_f32_16x16x32_bf16 v[108:111], v[190:193], v[140:143], v[108:111]
	v_mfma_f32_16x16x32_bf16 v[100:103], v[190:193], v[148:151], v[100:103]
	v_mfma_f32_16x16x32_bf16 v[92:95], v[200:203], v[140:143], v[92:95]
	v_mfma_f32_16x16x32_bf16 v[84:87], v[200:203], v[148:151], v[84:87]
	v_mfma_f32_16x16x32_bf16 v[68:71], v[208:211], v[140:143], v[68:71]
	v_mfma_f32_16x16x32_bf16 v[76:79], v[208:211], v[148:151], v[76:79]
	v_mfma_f32_16x16x32_bf16 v[124:127], v[186:189], v[144:147], v[124:127]
	v_mfma_f32_16x16x32_bf16 v[116:119], v[186:189], v[152:155], v[116:119]
	v_mfma_f32_16x16x32_bf16 v[108:111], v[196:199], v[144:147], v[108:111]
	v_mfma_f32_16x16x32_bf16 v[100:103], v[196:199], v[152:155], v[100:103]
	v_mfma_f32_16x16x32_bf16 v[92:95], v[204:207], v[144:147], v[92:95]
	v_mfma_f32_16x16x32_bf16 v[84:87], v[204:207], v[152:155], v[84:87]
	v_mfma_f32_16x16x32_bf16 v[68:71], v[212:215], v[144:147], v[68:71]
	v_mfma_f32_16x16x32_bf16 v[76:79], v[212:215], v[152:155], v[76:79]
	v_mfma_f32_16x16x32_bf16 v[120:123], v[182:185], v[156:159], v[120:123]
	v_mfma_f32_16x16x32_bf16 v[112:115], v[182:185], v[164:167], v[112:115]
	v_mfma_f32_16x16x32_bf16 v[104:107], v[190:193], v[156:159], v[104:107]
	v_mfma_f32_16x16x32_bf16 v[96:99], v[190:193], v[164:167], v[96:99]
	v_mfma_f32_16x16x32_bf16 v[88:91], v[200:203], v[156:159], v[88:91]
	v_mfma_f32_16x16x32_bf16 v[80:83], v[200:203], v[164:167], v[80:83]
	v_mfma_f32_16x16x32_bf16 v[64:67], v[208:211], v[156:159], v[64:67]
	v_mfma_f32_16x16x32_bf16 v[72:75], v[208:211], v[164:167], v[72:75]
	v_mfma_f32_16x16x32_bf16 v[120:123], v[186:189], v[160:163], v[120:123]
	v_mfma_f32_16x16x32_bf16 v[112:115], v[186:189], v[168:171], v[112:115]
	v_mfma_f32_16x16x32_bf16 v[104:107], v[196:199], v[160:163], v[104:107]
	v_mfma_f32_16x16x32_bf16 v[96:99], v[196:199], v[168:171], v[96:99]
	v_mfma_f32_16x16x32_bf16 v[88:91], v[204:207], v[160:163], v[88:91]
	v_mfma_f32_16x16x32_bf16 v[80:83], v[204:207], v[168:171], v[80:83]
	v_mfma_f32_16x16x32_bf16 v[64:67], v[212:215], v[160:163], v[64:67]
	v_mfma_f32_16x16x32_bf16 v[72:75], v[212:215], v[168:171], v[72:75]
	s_barrier
; #define PG8_LAS __attribute__((address_space(3)))
; #define PG8_STAGE(bufoff, gbase, voff) do { _Pragma("unroll") for (int _i = 0; _i < 2; ++_i) \
;         __builtin_amdgcn_global_load_lds((const unsigned*)((const char*)(gbase) + (voff)[_i]), (PG8_LAS unsigned*)(lds + (bufoff) + ldsw + _i * 8192), 16, 0, 0); } while (0)
; #define PG8_WAIT_V(n) asm volatile("s_waitcnt vmcnt(" #n ")" ::: "memory")
; #define PG8_WAIT_L(n) asm volatile("s_waitcnt lgkmcnt(" #n ")" ::: "memory")
; #define PG8_BAR __builtin_amdgcn_s_barrier()
;     __device__ __forceinline__ void operator()(const f32x4 (&acc)[2][2][4][2], const Unit& u, int wr, int wc, int fr, int fq) const {
;         const int lane = threadIdx.x & 63;
;         const int j0 = 128 * u.pn + 32 * wc + 2 * fr;
;         float wa[2][3], wb[2][3], ba[2], bb[2];
;         {
;             f32x2_t ta[3], tb[3];
; #pragma unroll
;             for (int k = 0; k < 3; ++k) { ta[k] = *(const f32x2_t*)(cw + k * NUP + j0); tb[k] = *(const f32x2_t*)(cw + k * NUP + DFF + j0); }
;             const f32x2_t tba = *(const f32x2_t*)(cb + j0), tbb = *(const f32x2_t*)(cb + DFF + j0);
; #pragma unroll
;             for (int n = 0; n < 2; ++n) {
; #pragma unroll
;                 for (int k = 0; k < 3; ++k) { wa[n][k] = ta[k][n]; wb[n][k] = tb[k][n]; }
;                 ba[n] = tba[n]; bb[n] = tbb[n]; }
;         }
;         if (fq == 3) {
; #pragma unroll
;             for (int ai = 0; ai < 2; ++ai)
; #pragma unroll
;                 for (int bj = 0; bj < 2; ++bj)
; #pragma unroll
;                     for (int n = 0; n < 2; ++n) { PG8_LAS float* hp = halo + (((((ai * 2 + wr) * 4 + wc) * 2 + bj) * 2 + n) * 32) + fr; hp[0] = acc[ai][bj][3][n][2]; hp[16] = acc[ai][bj][3][n][3]; }
;         }
;         asm volatile("s_waitcnt lgkmcnt(0)" ::: "memory"); __builtin_amdgcn_s_barrier(); asm volatile("" ::: "memory");
; template <class Epi, class Sched, bool ALIGN_EPI = false, bool SP2 = false>
; __device__ __forceinline__ void gemm_phase(PG8_LAS unsigned char* lds, const Gemm g, const Sched& S, const Epi& E) {
;     ...
;             PG8_LDA(At, 1, 1); PG8_STAGE(PG8_SB(1, 0), b3, voffB); PG8_STAGE(PG8_SB(1, 1), b3 + hstep, voffB); PG8_STAGE(PG8_SA(1, 0), a3, voffA);
;             PG8_WAIT_V(8); PG8_WAIT_L(0); PG8_BAR; PG8_MMA(1, 0, At, B0); PG8_MMA(1, 1, At, B1); PG8_BAR; PG8_SCHED;
;     ...
;         if constexpr (ALIGN_EPI) { if (wr == 0) PG8_BAR; }
	s_add_i32 s25, s82, s91
	v_lshl_add_u64 v[216:217], v[216:217], 0, s[54:55]
	s_mov_b32 m0, s25
	ds_read_b128 v[182:185], v180 offset:49152
	ds_read_b128 v[186:189], v180 offset:50176
	ds_read_b128 v[190:193], v180 offset:51200
	ds_read_b128 v[196:199], v180 offset:52224
	ds_read_b128 v[200:203], v180 offset:53248
	ds_read_b128 v[204:207], v180 offset:54272
	ds_read_b128 v[208:211], v180 offset:55296
	ds_read_b128 v[212:215], v180 offset:56320
	global_load_lds_dwordx4 v[216:217], off
	s_add_i32 m0, s25, 0x2000
	s_add_u32 s26, s78, 0x40080
	v_lshl_add_u64 v[216:217], v[218:219], 0, s[54:55]
	s_addc_u32 s27, s79, 0
	s_add_i32 s24, s24, s91
	global_load_lds_dwordx4 v[216:217], off
	v_lshl_add_u64 v[216:217], s[26:27], 0, v[128:129]
	s_mov_b32 m0, s24
	s_nop 0
	global_load_lds_dwordx4 v[216:217], off
	v_lshl_add_u64 v[216:217], s[26:27], 0, v[130:131]
	s_add_i32 m0, s24, 0x2000
	s_nop 0
	global_load_lds_dwordx4 v[216:217], off
	v_lshl_add_u64 v[216:217], v[220:221], 0, s[54:55]
	s_mov_b32 m0, s86
	s_nop 0
	global_load_lds_dwordx4 v[216:217], off
	v_lshl_add_u64 v[216:217], v[222:223], 0, s[54:55]
	s_mov_b32 m0, s83
	s_nop 0
	global_load_lds_dwordx4 v[216:217], off
	s_waitcnt vmcnt(8)
	s_waitcnt lgkmcnt(0)
	s_barrier
	s_waitcnt lgkmcnt(0)
	v_mfma_f32_16x16x32_bf16 v[60:63], v[182:185], v[140:143], v[60:63]
	v_mfma_f32_16x16x32_bf16 v[52:55], v[182:185], v[148:151], v[52:55]
	v_mfma_f32_16x16x32_bf16 v[44:47], v[190:193], v[140:143], v[44:47]
	v_mfma_f32_16x16x32_bf16 v[36:39], v[190:193], v[148:151], v[36:39]
	v_mfma_f32_16x16x32_bf16 v[28:31], v[200:203], v[140:143], v[28:31]
	v_mfma_f32_16x16x32_bf16 v[20:23], v[200:203], v[148:151], v[20:23]
	v_mfma_f32_16x16x32_bf16 v[0:3], v[208:211], v[140:143], v[0:3]
	v_mfma_f32_16x16x32_bf16 v[12:15], v[208:211], v[148:151], v[12:15]
	v_mfma_f32_16x16x32_bf16 v[60:63], v[186:189], v[144:147], v[60:63]
	v_mfma_f32_16x16x32_bf16 v[52:55], v[186:189], v[152:155], v[52:55]
	v_mfma_f32_16x16x32_bf16 v[44:47], v[196:199], v[144:147], v[44:47]
	v_mfma_f32_16x16x32_bf16 v[36:39], v[196:199], v[152:155], v[36:39]
	v_mfma_f32_16x16x32_bf16 v[28:31], v[204:207], v[144:147], v[28:31]
	v_mfma_f32_16x16x32_bf16 v[20:23], v[204:207], v[152:155], v[20:23]
	v_mfma_f32_16x16x32_bf16 v[0:3], v[212:215], v[144:147], v[0:3]
	v_mfma_f32_16x16x32_bf16 v[12:15], v[212:215], v[152:155], v[12:15]
	v_mfma_f32_16x16x32_bf16 v[56:59], v[182:185], v[156:159], v[56:59]
	v_mfma_f32_16x16x32_bf16 v[48:51], v[182:185], v[164:167], v[48:51]
	v_mfma_f32_16x16x32_bf16 v[40:43], v[190:193], v[156:159], v[40:43]
	v_mfma_f32_16x16x32_bf16 v[32:35], v[190:193], v[164:167], v[32:35]
	v_mfma_f32_16x16x32_bf16 v[24:27], v[200:203], v[156:159], v[24:27]
	v_mfma_f32_16x16x32_bf16 v[16:19], v[200:203], v[164:167], v[16:19]
	v_mfma_f32_16x16x32_bf16 v[4:7], v[208:211], v[156:159], v[4:7]
	v_mfma_f32_16x16x32_bf16 v[8:11], v[208:211], v[164:167], v[8:11]
	v_mfma_f32_16x16x32_bf16 v[56:59], v[186:189], v[160:163], v[56:59]
	v_mfma_f32_16x16x32_bf16 v[48:51], v[186:189], v[168:171], v[48:51]
	v_mfma_f32_16x16x32_bf16 v[40:43], v[196:199], v[160:163], v[40:43]
	v_mfma_f32_16x16x32_bf16 v[32:35], v[196:199], v[168:171], v[32:35]
	v_mfma_f32_16x16x32_bf16 v[24:27], v[204:207], v[160:163], v[24:27]
	v_mfma_f32_16x16x32_bf16 v[16:19], v[204:207], v[168:171], v[16:19]
	v_mfma_f32_16x16x32_bf16 v[4:7], v[212:215], v[160:163], v[4:7]
	v_mfma_f32_16x16x32_bf16 v[8:11], v[212:215], v[168:171], v[8:11]
	s_barrier
	s_add_i32 vcc_hi, vcc_hi, 2
	s_add_u32 s76, s76, 0x100
	s_addc_u32 s77, s77, 0
	s_add_u32 s75, s75, 0x100
	s_addc_u32 vcc_lo, vcc_lo, 0
	s_cmp_gt_u32 vcc_hi, 13
	s_cbranch_scc0 .LBB0_886
	s_and_b64 vcc, exec, s[56:57]
	s_cbranch_vccz .LBB0_889
	s_barrier
.LBB0_889:
	s_setprio 0
	v_readfirstlane_b32 s19, v195
	v_and_b32_e32 v190, 15, v195
	v_bfe_u32 v191, v195, 4, 2
	s_lshr_b32 s19, s19, 6
	s_and_b32 s24, s19, 3
	s_lshr_b32 s25, s19, 2
	v_lshrrev_b32_e32 v192, 2, v237
	s_lshl_b32 s27, s25, 6
	v_lshl_add_u32 v193, v191, 2, s27
	v_mul_u32_u24_e32 v193, 0x1600, v193
	v_lshl_add_u32 v157, v192, 1, v193
	v_add_u32_e32 v158, 48, v195
	v_and_b32_e32 v158, 63, v158
	v_lshlrev_b32_e32 v158, 2, v158
	s_lshl_b32 s27, s25, 11
	s_lshl_b32 s17, s24, 9
	s_add_i32 s27, s27, s17
	s_add_i32 s27, s27, 0x20400
	v_lshl_add_u32 v159, v190, 2, s27
	v_add_u32_e32 v160, 0xfffff800, v159
	v_mov_b32_e32 v162, 1.0
	v_mov_b32_e32 v163, 1.0
	s_and_saveexec_b64 s[16:17], s[6:7]
	ds_write_b32 v159, v70
	ds_write_b32 v159, v71 offset:64
	ds_write_b32 v159, v78 offset:128
	ds_write_b32 v159, v79 offset:192
	ds_write_b32 v159, v66 offset:256
	ds_write_b32 v159, v67 offset:320
	ds_write_b32 v159, v74 offset:384
	ds_write_b32 v159, v75 offset:448
	ds_write_b32 v159, v2 offset:4096
	ds_write_b32 v159, v3 offset:4160
	ds_write_b32 v159, v14 offset:4224
	ds_write_b32 v159, v15 offset:4288
	ds_write_b32 v159, v6 offset:4352
	ds_write_b32 v159, v7 offset:4416
	s_waitcnt lgkmcnt(13)
	ds_write_b32 v159, v10 offset:4480
	s_waitcnt lgkmcnt(13)
	ds_write_b32 v159, v11 offset:4544
	s_or_b64 exec, exec, s[16:17]
	s_waitcnt lgkmcnt(0)
	s_barrier
	s_cmp_eq_u32 s25, 0
	s_cbranch_scc1 .Lp8_nohalo
	ds_read_b32 v228, v160
	ds_read_b32 v229, v160 offset:64
	ds_read_b32 v230, v160 offset:256
	ds_read_b32 v231, v160 offset:320
	ds_read_b32 v232, v160 offset:128
	ds_read_b32 v233, v160 offset:192
	ds_read_b32 v234, v160 offset:384
	ds_read_b32 v235, v160 offset:448
	s_branch .Lp8_halo_done

;     __device__ __forceinline__ void operator()(const f32x4 (&acc)[2][2][4][2], const Unit& u, int wr, int wc, int fr, int fq) const {
;     ...
;         const int src = ((lane - 16) & 63) * 4;
; #pragma unroll
;         for (int ai = 0; ai < 2; ++ai) {
;             const int blk = 2 * ai + wr;
; #pragma unroll
;             for (int m = 0; m < 4; ++m) {
;                 float o[2][4];
; #pragma unroll
;                 for (int n = 0; n < 2; ++n) {
;                     const f32x4 Xa = acc[ai][0][m][n], Xb = acc[ai][1][m][n];
;                     float da2, da3, db2, db3;
;                     if (m > 0) { const bool t = (fq == 3); da2 = t ? acc[ai][0][m > 0 ? m - 1 : 0][n][2] : Xa[2]; da3 = t ? acc[ai][0][m > 0 ? m - 1 : 0][n][3] : Xa[3];
;                                  db2 = t ? acc[ai][1][m > 0 ? m - 1 : 0][n][2] : Xb[2]; db3 = t ? acc[ai][1][m > 0 ? m - 1 : 0][n][3] : Xb[3]; }
;                     else { da2 = Xa[2]; da3 = Xa[3]; db2 = Xb[2]; db3 = Xb[3]; }
;                     float Ha2 = __builtin_bit_cast(float, __builtin_amdgcn_ds_bpermute(src, __builtin_bit_cast(int, da2)));
;                     float Ha3 = __builtin_bit_cast(float, __builtin_amdgcn_ds_bpermute(src, __builtin_bit_cast(int, da3)));
;                     float Hb2 = __builtin_bit_cast(float, __builtin_amdgcn_ds_bpermute(src, __builtin_bit_cast(int, db2)));
;                     float Hb3 = __builtin_bit_cast(float, __builtin_amdgcn_ds_bpermute(src, __builtin_bit_cast(int, db3)));
;                     if (m == 0) {
;                         float h2a = 0.f, h3a = 0.f, h2b = 0.f, h3b = 0.f;
;                         if (blk > 0) { const PG8_LAS float* hp = halo + ((((blk - 1) * 4 + wc) * 2 + 0) * 2 + n) * 32 + fr; h2a = hp[0]; h3a = hp[16]; h2b = hp[64]; h3b = hp[80]; }
;                         if (fq == 0) { Ha2 = h2a; Ha3 = h3a; Hb2 = h2b; Hb3 = h3b; }
;                     }
;                     const f32x2_t W0 = {wa[n][0], wb[n][0]}, W1 = {wa[n][1], wb[n][1]}, W2 = {wa[n][2], wb[n][2]}, B2 = {ba[n], bb[n]};
;                     const f32x2_t H2 = {Ha2, Hb2}, H3 = {Ha3, Hb3}, X0 = {Xa[0], Xb[0]}, X1 = {Xa[1], Xb[1]}, X2 = {Xa[2], Xb[2]}, X3 = {Xa[3], Xb[3]};
;                     const f32x2_t y0 = B2 + W0 * H2 + W1 * H3 + W2 * X0, y1 = B2 + W0 * H3 + W1 * X0 + W2 * X1, y2 = B2 + W0 * X0 + W1 * X1 + W2 * X2, y3 = B2 + W0 * X1 + W1 * X2 + W2 * X3;
.Lp8_side_done:
	s_mul_i32 s76, s74, 0x160000
	s_add_u32 s76, s40, s76
	s_addc_u32 s77, s41, 0
	s_waitcnt lgkmcnt(13)
	ds_bpermute_b32 v204, v158, v110
	s_waitcnt lgkmcnt(13)
	ds_bpermute_b32 v205, v158, v111
	s_waitcnt lgkmcnt(13)
	ds_bpermute_b32 v206, v158, v106
	s_waitcnt lgkmcnt(13)
	ds_bpermute_b32 v207, v158, v107
	s_waitcnt lgkmcnt(13)
	ds_bpermute_b32 v208, v158, v102
	s_waitcnt lgkmcnt(13)
	ds_bpermute_b32 v209, v158, v103
	s_waitcnt lgkmcnt(13)
	ds_bpermute_b32 v210, v158, v98
	s_waitcnt lgkmcnt(13)
	ds_bpermute_b32 v211, v158, v99
	s_waitcnt lgkmcnt(12)
	v_cndmask_b32_e64 v140, v196, v228, s[8:9]
	v_cndmask_b32_e64 v141, v197, v229, s[8:9]
	v_cndmask_b32_e64 v142, v198, v230, s[8:9]
	v_cndmask_b32_e64 v143, v199, v231, s[8:9]
	v_pk_fma_f32 v[164:165], v[238:239], v[140:141], v[250:251] op_sel_hi:[0,1,0]
	v_pk_fma_f32 v[168:169], v[244:245], v[142:143], v[252:253] op_sel_hi:[0,1,0]
	v_pk_fma_f32 v[166:167], v[238:239], v[124:125], v[250:251] op_sel_hi:[0,1,0]
	v_pk_fma_f32 v[170:171], v[244:245], v[120:121], v[252:253] op_sel_hi:[0,1,0]
	v_pk_fma_f32 v[164:165], v[242:243], v[124:125], v[164:165] op_sel_hi:[0,1,1]
	v_pk_fma_f32 v[168:169], v[248:249], v[120:121], v[168:169] op_sel_hi:[0,1,1]
	v_pk_fma_f32 v[166:167], v[242:243], v[126:127], v[166:167] op_sel_hi:[0,1,1]
	v_pk_fma_f32 v[170:171], v[248:249], v[122:123], v[170:171] op_sel_hi:[0,1,1]
	v_fmac_f32_e32 v164, v240, v141
	v_fmac_f32_e32 v168, v246, v143
	v_fmac_f32_e32 v165, v240, v124
	v_fmac_f32_e32 v169, v246, v120
	v_fmac_f32_e32 v166, v240, v125
	v_fmac_f32_e32 v170, v246, v121
	v_fmac_f32_e32 v167, v240, v126
	v_fmac_f32_e32 v171, v246, v122
	v_exp_f32_e32 v144, v164
	v_exp_f32_e32 v145, v165
	v_exp_f32_e32 v146, v166
	v_exp_f32_e32 v147, v167
	v_pk_mul_f32 v[164:165], v[164:165], v[168:169]
	v_pk_mul_f32 v[166:167], v[166:167], v[170:171]
	v_pk_add_f32 v[144:145], v[144:145], v[162:163]
	v_pk_add_f32 v[146:147], v[146:147], v[162:163]
	v_rcp_f32_e32 v144, v144
	v_rcp_f32_e32 v145, v145
	v_rcp_f32_e32 v146, v146
	v_rcp_f32_e32 v147, v147
	s_waitcnt lgkmcnt(8)
	v_cndmask_b32_e64 v140, v200, v232, s[8:9]
	v_cndmask_b32_e64 v141, v201, v233, s[8:9]
	v_cndmask_b32_e64 v142, v202, v234, s[8:9]
	v_cndmask_b32_e64 v143, v203, v235, s[8:9]
	v_pk_fma_f32 v[182:183], v[238:239], v[140:141], v[250:251] op_sel:[1,0,1] op_sel_hi:[1,1,1]
	v_pk_fma_f32 v[186:187], v[244:245], v[142:143], v[252:253] op_sel:[1,0,1] op_sel_hi:[1,1,1]
	v_pk_fma_f32 v[184:185], v[238:239], v[116:117], v[250:251] op_sel:[1,0,1] op_sel_hi:[1,1,1]
	v_pk_fma_f32 v[188:189], v[244:245], v[112:113], v[252:253] op_sel:[1,0,1] op_sel_hi:[1,1,1]
	v_pk_fma_f32 v[182:183], v[242:243], v[116:117], v[182:183] op_sel:[1,0,0] op_sel_hi:[1,1,1]
	v_pk_fma_f32 v[186:187], v[248:249], v[112:113], v[186:187] op_sel:[1,0,0] op_sel_hi:[1,1,1]
	v_pk_fma_f32 v[184:185], v[242:243], v[118:119], v[184:185] op_sel:[1,0,0] op_sel_hi:[1,1,1]
	v_pk_fma_f32 v[188:189], v[248:249], v[114:115], v[188:189] op_sel:[1,0,0] op_sel_hi:[1,1,1]
	v_fmac_f32_e32 v182, v241, v141
	v_fmac_f32_e32 v186, v247, v143
	v_fmac_f32_e32 v183, v241, v116
	v_fmac_f32_e32 v187, v247, v112
	v_fmac_f32_e32 v184, v241, v117
	v_fmac_f32_e32 v188, v247, v113
	v_fmac_f32_e32 v185, v241, v118
	v_fmac_f32_e32 v189, v247, v114
	v_exp_f32_e32 v148, v182
	v_exp_f32_e32 v149, v183
	v_exp_f32_e32 v150, v184
	v_exp_f32_e32 v151, v185
	v_pk_mul_f32 v[182:183], v[182:183], v[186:187]
	v_pk_mul_f32 v[184:185], v[184:185], v[188:189]
	v_pk_add_f32 v[148:149], v[148:149], v[162:163]
	v_pk_add_f32 v[150:151], v[150:151], v[162:163]
	v_rcp_f32_e32 v148, v148
	v_rcp_f32_e32 v149, v149
	v_rcp_f32_e32 v150, v150
	v_rcp_f32_e32 v151, v151
	v_pk_mul_f32 v[164:165], v[164:165], v[144:145]
	v_pk_mul_f32 v[166:167], v[166:167], v[146:147]
	v_pk_mul_f32 v[182:183], v[182:183], v[148:149]
	v_pk_mul_f32 v[184:185], v[184:185], v[150:151]
	v_cvt_pk_bf16_f32 v152, v164, v182
	v_cvt_pk_bf16_f32 v153, v165, v183
	v_cvt_pk_bf16_f32 v154, v166, v184
	v_cvt_pk_bf16_f32 v155, v167, v185
	global_store_dword v157, v152, s[76:77]
	s_add_u32 s76, s76, 0x1600
	s_addc_u32 s77, s77, 0
	global_store_dword v157, v153, s[76:77]
	s_add_u32 s76, s76, 0x1600
	s_addc_u32 s77, s77, 0
	global_store_dword v157, v154, s[76:77]
	s_add_u32 s76, s76, 0x1600
	s_addc_u32 s77, s77, 0
	global_store_dword v157, v155, s[76:77]
	s_add_u32 s76, s76, 0x11e00
	s_addc_u32 s77, s77, 0
	ds_bpermute_b32 v212, v158, v94
	ds_bpermute_b32 v213, v158, v95
	ds_bpermute_b32 v214, v158, v90
	ds_bpermute_b32 v215, v158, v91
	ds_bpermute_b32 v216, v158, v86
	ds_bpermute_b32 v217, v158, v87
	s_waitcnt lgkmcnt(13)
	ds_bpermute_b32 v218, v158, v82
	s_waitcnt lgkmcnt(13)
	ds_bpermute_b32 v219, v158, v83
	s_waitcnt lgkmcnt(13)
	ds_read_b32 v228, v159 offset:2048
	s_waitcnt lgkmcnt(13)
	ds_read_b32 v229, v159 offset:2112
	s_waitcnt lgkmcnt(13)
	ds_read_b32 v230, v159 offset:2304
	s_waitcnt lgkmcnt(13)
	ds_read_b32 v231, v159 offset:2368
	s_waitcnt lgkmcnt(13)
	ds_read_b32 v232, v159 offset:2176
	s_waitcnt lgkmcnt(13)
	ds_read_b32 v233, v159 offset:2240
	s_waitcnt lgkmcnt(13)
	ds_read_b32 v234, v159 offset:2432
	s_waitcnt lgkmcnt(13)
;     __device__ __forceinline__ void operator()(const f32x4 (&acc)[2][2][4][2], const Unit& u, int wr, int wc, int fr, int fq) const {
;     ...
;                 for (int n = 0; n < 2; ++n) {
;                     const f32x4 Xa = acc[ai][0][m][n], Xb = acc[ai][1][m][n];
;                     float da2, da3, db2, db3;
;                     if (m > 0) { const bool t = (fq == 3); da2 = t ? acc[ai][0][m > 0 ? m - 1 : 0][n][2] : Xa[2]; da3 = t ? acc[ai][0][m > 0 ? m - 1 : 0][n][3] : Xa[3];
;                                  db2 = t ? acc[ai][1][m > 0 ? m - 1 : 0][n][2] : Xb[2]; db3 = t ? acc[ai][1][m > 0 ? m - 1 : 0][n][3] : Xb[3]; }
;                     else { da2 = Xa[2]; da3 = Xa[3]; db2 = Xb[2]; db3 = Xb[3]; }
;                     float Ha2 = __builtin_bit_cast(float, __builtin_amdgcn_ds_bpermute(src, __builtin_bit_cast(int, da2)));
;                     float Ha3 = __builtin_bit_cast(float, __builtin_amdgcn_ds_bpermute(src, __builtin_bit_cast(int, da3)));
;                     float Hb2 = __builtin_bit_cast(float, __builtin_amdgcn_ds_bpermute(src, __builtin_bit_cast(int, db2)));
;                     float Hb3 = __builtin_bit_cast(float, __builtin_amdgcn_ds_bpermute(src, __builtin_bit_cast(int, db3)));
;                     if (m == 0) {
;                         float h2a = 0.f, h3a = 0.f, h2b = 0.f, h3b = 0.f;
;                         if (blk > 0) { const PG8_LAS float* hp = halo + ((((blk - 1) * 4 + wc) * 2 + 0) * 2 + n) * 32 + fr; h2a = hp[0]; h3a = hp[16]; h2b = hp[64]; h3b = hp[80]; }
;                         if (fq == 0) { Ha2 = h2a; Ha3 = h3a; Hb2 = h2b; Hb3 = h3b; }
;                     }
;                     const f32x2_t W0 = {wa[n][0], wb[n][0]}, W1 = {wa[n][1], wb[n][1]}, W2 = {wa[n][2], wb[n][2]}, B2 = {ba[n], bb[n]};
;                     const f32x2_t H2 = {Ha2, Hb2}, H3 = {Ha3, Hb3}, X0 = {Xa[0], Xb[0]}, X1 = {Xa[1], Xb[1]}, X2 = {Xa[2], Xb[2]}, X3 = {Xa[3], Xb[3]};
;                     const f32x2_t y0 = B2 + W0 * H2 + W1 * H3 + W2 * X0, y1 = B2 + W0 * H3 + W1 * X0 + W2 * X1, y2 = B2 + W0 * X0 + W1 * X1 + W2 * X2, y3 = B2 + W0 * X1 + W1 * X2 + W2 * X3;
;                     const float ya0 = y0[0], yb0 = y0[1], ya1 = y1[0], yb1 = y1[1], ya2 = y2[0], yb2 = y2[1], ya3 = y3[0], yb3 = y3[1];
;                     o[n][0] = silu_f(ya0) * yb0; o[n][1] = silu_f(ya1) * yb1; o[n][2] = silu_f(ya2) * yb2; o[n][3] = silu_f(ya3) * yb3;
	ds_read_b32 v235, v159 offset:2496
	v_cndmask_b32_e64 v140, v204, v196, s[8:9]
	v_cndmask_b32_e64 v141, v205, v197, s[8:9]
	v_cndmask_b32_e64 v142, v206, v198, s[8:9]
	v_cndmask_b32_e64 v143, v207, v199, s[8:9]
	v_pk_fma_f32 v[164:165], v[238:239], v[140:141], v[250:251] op_sel_hi:[0,1,0]
	v_pk_fma_f32 v[168:169], v[244:245], v[142:143], v[252:253] op_sel_hi:[0,1,0]
	v_pk_fma_f32 v[166:167], v[238:239], v[108:109], v[250:251] op_sel_hi:[0,1,0]
	v_pk_fma_f32 v[170:171], v[244:245], v[104:105], v[252:253] op_sel_hi:[0,1,0]
	v_pk_fma_f32 v[164:165], v[242:243], v[108:109], v[164:165] op_sel_hi:[0,1,1]
	v_pk_fma_f32 v[168:169], v[248:249], v[104:105], v[168:169] op_sel_hi:[0,1,1]
	v_pk_fma_f32 v[166:167], v[242:243], v[110:111], v[166:167] op_sel_hi:[0,1,1]
	v_pk_fma_f32 v[170:171], v[248:249], v[106:107], v[170:171] op_sel_hi:[0,1,1]
	v_fmac_f32_e32 v164, v240, v141
	v_fmac_f32_e32 v168, v246, v143
	v_fmac_f32_e32 v165, v240, v108
	v_fmac_f32_e32 v169, v246, v104
	v_fmac_f32_e32 v166, v240, v109
	v_fmac_f32_e32 v170, v246, v105
	v_fmac_f32_e32 v167, v240, v110
	v_fmac_f32_e32 v171, v246, v106
	v_exp_f32_e32 v144, v164
	v_exp_f32_e32 v145, v165
	v_exp_f32_e32 v146, v166
	v_exp_f32_e32 v147, v167
	v_pk_mul_f32 v[164:165], v[164:165], v[168:169]
	v_pk_mul_f32 v[166:167], v[166:167], v[170:171]
	v_pk_add_f32 v[144:145], v[144:145], v[162:163]
	v_pk_add_f32 v[146:147], v[146:147], v[162:163]
	v_rcp_f32_e32 v144, v144
	v_rcp_f32_e32 v145, v145
	v_rcp_f32_e32 v146, v146
	v_rcp_f32_e32 v147, v147
	v_cndmask_b32_e64 v140, v208, v200, s[8:9]
	v_cndmask_b32_e64 v141, v209, v201, s[8:9]
	v_cndmask_b32_e64 v142, v210, v202, s[8:9]
	v_cndmask_b32_e64 v143, v211, v203, s[8:9]
	v_pk_fma_f32 v[182:183], v[238:239], v[140:141], v[250:251] op_sel:[1,0,1] op_sel_hi:[1,1,1]
	v_pk_fma_f32 v[186:187], v[244:245], v[142:143], v[252:253] op_sel:[1,0,1] op_sel_hi:[1,1,1]
	v_pk_fma_f32 v[184:185], v[238:239], v[100:101], v[250:251] op_sel:[1,0,1] op_sel_hi:[1,1,1]
	v_pk_fma_f32 v[188:189], v[244:245], v[96:97], v[252:253] op_sel:[1,0,1] op_sel_hi:[1,1,1]
	v_pk_fma_f32 v[182:183], v[242:243], v[100:101], v[182:183] op_sel:[1,0,0] op_sel_hi:[1,1,1]
	v_pk_fma_f32 v[186:187], v[248:249], v[96:97], v[186:187] op_sel:[1,0,0] op_sel_hi:[1,1,1]
	v_pk_fma_f32 v[184:185], v[242:243], v[102:103], v[184:185] op_sel:[1,0,0] op_sel_hi:[1,1,1]
	v_pk_fma_f32 v[188:189], v[248:249], v[98:99], v[188:189] op_sel:[1,0,0] op_sel_hi:[1,1,1]
	v_fmac_f32_e32 v182, v241, v141
	v_fmac_f32_e32 v186, v247, v143
	v_fmac_f32_e32 v183, v241, v100
	v_fmac_f32_e32 v187, v247, v96
	v_fmac_f32_e32 v184, v241, v101
	v_fmac_f32_e32 v188, v247, v97
	v_fmac_f32_e32 v185, v241, v102
	v_fmac_f32_e32 v189, v247, v98
	v_exp_f32_e32 v148, v182
	v_exp_f32_e32 v149, v183
	v_exp_f32_e32 v150, v184
	v_exp_f32_e32 v151, v185
	v_pk_mul_f32 v[182:183], v[182:183], v[186:187]
	v_pk_mul_f32 v[184:185], v[184:185], v[188:189]
	v_pk_add_f32 v[148:149], v[148:149], v[162:163]
	v_pk_add_f32 v[150:151], v[150:151], v[162:163]
	v_rcp_f32_e32 v148, v148
	v_rcp_f32_e32 v149, v149
	v_rcp_f32_e32 v150, v150
	v_rcp_f32_e32 v151, v151
	v_pk_mul_f32 v[164:165], v[164:165], v[144:145]
	v_pk_mul_f32 v[166:167], v[166:167], v[146:147]
	v_pk_mul_f32 v[182:183], v[182:183], v[148:149]
	v_pk_mul_f32 v[184:185], v[184:185], v[150:151]
	v_cvt_pk_bf16_f32 v152, v164, v182
	v_cvt_pk_bf16_f32 v153, v165, v183
	v_cvt_pk_bf16_f32 v154, v166, v184
	v_cvt_pk_bf16_f32 v155, v167, v185
	global_store_dword v157, v152, s[76:77]
	s_add_u32 s76, s76, 0x1600
	s_addc_u32 s77, s77, 0
	global_store_dword v157, v153, s[76:77]
	s_add_u32 s76, s76, 0x1600
	s_addc_u32 s77, s77, 0
	global_store_dword v157, v154, s[76:77]
	s_add_u32 s76, s76, 0x1600
	s_addc_u32 s77, s77, 0
	global_store_dword v157, v155, s[76:77]
	s_add_u32 s76, s76, 0x11e00
	s_addc_u32 s77, s77, 0
	s_waitcnt lgkmcnt(13)
	ds_bpermute_b32 v220, v158, v70
	s_waitcnt lgkmcnt(13)
	ds_bpermute_b32 v221, v158, v71
	s_waitcnt lgkmcnt(13)
	ds_bpermute_b32 v222, v158, v66
	s_waitcnt lgkmcnt(13)
	ds_bpermute_b32 v223, v158, v67
	s_waitcnt lgkmcnt(13)
	ds_bpermute_b32 v224, v158, v78
	s_waitcnt lgkmcnt(13)
	ds_bpermute_b32 v225, v158, v79
	s_waitcnt lgkmcnt(13)
	ds_bpermute_b32 v226, v158, v74
	s_waitcnt lgkmcnt(13)
	ds_bpermute_b32 v227, v158, v75
	v_cndmask_b32_e64 v140, v212, v204, s[8:9]
	v_cndmask_b32_e64 v141, v213, v205, s[8:9]
	v_cndmask_b32_e64 v142, v214, v206, s[8:9]
	v_cndmask_b32_e64 v143, v215, v207, s[8:9]
	v_pk_fma_f32 v[164:165], v[238:239], v[140:141], v[250:251] op_sel_hi:[0,1,0]
	v_pk_fma_f32 v[168:169], v[244:245], v[142:143], v[252:253] op_sel_hi:[0,1,0]
	v_pk_fma_f32 v[166:167], v[238:239], v[92:93], v[250:251] op_sel_hi:[0,1,0]
	v_pk_fma_f32 v[170:171], v[244:245], v[88:89], v[252:253] op_sel_hi:[0,1,0]
	v_pk_fma_f32 v[164:165], v[242:243], v[92:93], v[164:165] op_sel_hi:[0,1,1]
	v_pk_fma_f32 v[168:169], v[248:249], v[88:89], v[168:169] op_sel_hi:[0,1,1]
	v_pk_fma_f32 v[166:167], v[242:243], v[94:95], v[166:167] op_sel_hi:[0,1,1]
	v_pk_fma_f32 v[170:171], v[248:249], v[90:91], v[170:171] op_sel_hi:[0,1,1]
	v_fmac_f32_e32 v164, v240, v141
	v_fmac_f32_e32 v168, v246, v143
	v_fmac_f32_e32 v165, v240, v92
	v_fmac_f32_e32 v169, v246, v88
	v_fmac_f32_e32 v166, v240, v93
	v_fmac_f32_e32 v170, v246, v89
	v_fmac_f32_e32 v167, v240, v94
	v_fmac_f32_e32 v171, v246, v90
	v_exp_f32_e32 v144, v164
	v_exp_f32_e32 v145, v165
	v_exp_f32_e32 v146, v166
	v_exp_f32_e32 v147, v167
	v_pk_mul_f32 v[164:165], v[164:165], v[168:169]
	v_pk_mul_f32 v[166:167], v[166:167], v[170:171]
	v_pk_add_f32 v[144:145], v[144:145], v[162:163]
	v_pk_add_f32 v[146:147], v[146:147], v[162:163]
	v_rcp_f32_e32 v144, v144
;     __device__ __forceinline__ void operator()(const f32x4 (&acc)[2][2][4][2], const Unit& u, int wr, int wc, int fr, int fq) const {
;     ...
;                 for (int n = 0; n < 2; ++n) {
;                     const f32x4 Xa = acc[ai][0][m][n], Xb = acc[ai][1][m][n];
;                     float da2, da3, db2, db3;
;                     if (m > 0) { const bool t = (fq == 3); da2 = t ? acc[ai][0][m > 0 ? m - 1 : 0][n][2] : Xa[2]; da3 = t ? acc[ai][0][m > 0 ? m - 1 : 0][n][3] : Xa[3];
;                                  db2 = t ? acc[ai][1][m > 0 ? m - 1 : 0][n][2] : Xb[2]; db3 = t ? acc[ai][1][m > 0 ? m - 1 : 0][n][3] : Xb[3]; }
;                     else { da2 = Xa[2]; da3 = Xa[3]; db2 = Xb[2]; db3 = Xb[3]; }
;                     float Ha2 = __builtin_bit_cast(float, __builtin_amdgcn_ds_bpermute(src, __builtin_bit_cast(int, da2)));
;                     float Ha3 = __builtin_bit_cast(float, __builtin_amdgcn_ds_bpermute(src, __builtin_bit_cast(int, da3)));
;                     float Hb2 = __builtin_bit_cast(float, __builtin_amdgcn_ds_bpermute(src, __builtin_bit_cast(int, db2)));
;                     float Hb3 = __builtin_bit_cast(float, __builtin_amdgcn_ds_bpermute(src, __builtin_bit_cast(int, db3)));
;                     if (m == 0) {
;                         float h2a = 0.f, h3a = 0.f, h2b = 0.f, h3b = 0.f;
;                         if (blk > 0) { const PG8_LAS float* hp = halo + ((((blk - 1) * 4 + wc) * 2 + 0) * 2 + n) * 32 + fr; h2a = hp[0]; h3a = hp[16]; h2b = hp[64]; h3b = hp[80]; }
;                         if (fq == 0) { Ha2 = h2a; Ha3 = h3a; Hb2 = h2b; Hb3 = h3b; }
;                     }
;                     const f32x2_t W0 = {wa[n][0], wb[n][0]}, W1 = {wa[n][1], wb[n][1]}, W2 = {wa[n][2], wb[n][2]}, B2 = {ba[n], bb[n]};
;                     const f32x2_t H2 = {Ha2, Hb2}, H3 = {Ha3, Hb3}, X0 = {Xa[0], Xb[0]}, X1 = {Xa[1], Xb[1]}, X2 = {Xa[2], Xb[2]}, X3 = {Xa[3], Xb[3]};
;                     const f32x2_t y0 = B2 + W0 * H2 + W1 * H3 + W2 * X0, y1 = B2 + W0 * H3 + W1 * X0 + W2 * X1, y2 = B2 + W0 * X0 + W1 * X1 + W2 * X2, y3 = B2 + W0 * X1 + W1 * X2 + W2 * X3;
;                     const float ya0 = y0[0], yb0 = y0[1], ya1 = y1[0], yb1 = y1[1], ya2 = y2[0], yb2 = y2[1], ya3 = y3[0], yb3 = y3[1];
;                     o[n][0] = silu_f(ya0) * yb0; o[n][1] = silu_f(ya1) * yb1; o[n][2] = silu_f(ya2) * yb2; o[n][3] = silu_f(ya3) * yb3;
	v_rcp_f32_e32 v145, v145
	v_rcp_f32_e32 v146, v146
	v_rcp_f32_e32 v147, v147
	v_cndmask_b32_e64 v140, v216, v208, s[8:9]
	v_cndmask_b32_e64 v141, v217, v209, s[8:9]
	v_cndmask_b32_e64 v142, v218, v210, s[8:9]
	v_cndmask_b32_e64 v143, v219, v211, s[8:9]
	v_pk_fma_f32 v[182:183], v[238:239], v[140:141], v[250:251] op_sel:[1,0,1] op_sel_hi:[1,1,1]
	v_pk_fma_f32 v[186:187], v[244:245], v[142:143], v[252:253] op_sel:[1,0,1] op_sel_hi:[1,1,1]
	v_pk_fma_f32 v[184:185], v[238:239], v[84:85], v[250:251] op_sel:[1,0,1] op_sel_hi:[1,1,1]
	v_pk_fma_f32 v[188:189], v[244:245], v[80:81], v[252:253] op_sel:[1,0,1] op_sel_hi:[1,1,1]
	v_pk_fma_f32 v[182:183], v[242:243], v[84:85], v[182:183] op_sel:[1,0,0] op_sel_hi:[1,1,1]
	v_pk_fma_f32 v[186:187], v[248:249], v[80:81], v[186:187] op_sel:[1,0,0] op_sel_hi:[1,1,1]
	v_pk_fma_f32 v[184:185], v[242:243], v[86:87], v[184:185] op_sel:[1,0,0] op_sel_hi:[1,1,1]
	v_pk_fma_f32 v[188:189], v[248:249], v[82:83], v[188:189] op_sel:[1,0,0] op_sel_hi:[1,1,1]
	v_fmac_f32_e32 v182, v241, v141
	v_fmac_f32_e32 v186, v247, v143
	v_fmac_f32_e32 v183, v241, v84
	v_fmac_f32_e32 v187, v247, v80
	v_fmac_f32_e32 v184, v241, v85
	v_fmac_f32_e32 v188, v247, v81
	v_fmac_f32_e32 v185, v241, v86
	v_fmac_f32_e32 v189, v247, v82
	v_exp_f32_e32 v148, v182
	v_exp_f32_e32 v149, v183
	v_exp_f32_e32 v150, v184
	v_exp_f32_e32 v151, v185
	v_pk_mul_f32 v[182:183], v[182:183], v[186:187]
	v_pk_mul_f32 v[184:185], v[184:185], v[188:189]
	v_pk_add_f32 v[148:149], v[148:149], v[162:163]
	v_pk_add_f32 v[150:151], v[150:151], v[162:163]
	v_rcp_f32_e32 v148, v148
	v_rcp_f32_e32 v149, v149
	v_rcp_f32_e32 v150, v150
	v_rcp_f32_e32 v151, v151
	v_pk_mul_f32 v[164:165], v[164:165], v[144:145]
	v_pk_mul_f32 v[166:167], v[166:167], v[146:147]
	v_pk_mul_f32 v[182:183], v[182:183], v[148:149]
	v_pk_mul_f32 v[184:185], v[184:185], v[150:151]
	v_cvt_pk_bf16_f32 v152, v164, v182
	v_cvt_pk_bf16_f32 v153, v165, v183
	v_cvt_pk_bf16_f32 v154, v166, v184
	v_cvt_pk_bf16_f32 v155, v167, v185
	global_store_dword v157, v152, s[76:77]
	s_add_u32 s76, s76, 0x1600
	s_addc_u32 s77, s77, 0
	global_store_dword v157, v153, s[76:77]
	s_add_u32 s76, s76, 0x1600
	s_addc_u32 s77, s77, 0
	global_store_dword v157, v154, s[76:77]
	s_add_u32 s76, s76, 0x1600
	s_addc_u32 s77, s77, 0
	global_store_dword v157, v155, s[76:77]
	s_add_u32 s76, s76, 0x11e00
	s_addc_u32 s77, s77, 0
	s_waitcnt lgkmcnt(13)
	ds_bpermute_b32 v196, v158, v62
	s_waitcnt lgkmcnt(13)
	ds_bpermute_b32 v197, v158, v63
	s_waitcnt lgkmcnt(13)
	ds_bpermute_b32 v198, v158, v58
	s_waitcnt lgkmcnt(13)
	ds_bpermute_b32 v199, v158, v59
	s_waitcnt lgkmcnt(13)
	ds_bpermute_b32 v200, v158, v54
	s_waitcnt lgkmcnt(13)
	ds_bpermute_b32 v201, v158, v55
	s_waitcnt lgkmcnt(13)
	ds_bpermute_b32 v202, v158, v50
	s_waitcnt lgkmcnt(13)
	ds_bpermute_b32 v203, v158, v51
	s_waitcnt lgkmcnt(12)
	v_cndmask_b32_e64 v140, v220, v212, s[8:9]
	v_cndmask_b32_e64 v141, v221, v213, s[8:9]
	v_cndmask_b32_e64 v142, v222, v214, s[8:9]
	v_cndmask_b32_e64 v143, v223, v215, s[8:9]
	v_pk_fma_f32 v[164:165], v[238:239], v[140:141], v[250:251] op_sel_hi:[0,1,0]
	v_pk_fma_f32 v[168:169], v[244:245], v[142:143], v[252:253] op_sel_hi:[0,1,0]
	v_pk_fma_f32 v[166:167], v[238:239], v[68:69], v[250:251] op_sel_hi:[0,1,0]
	v_pk_fma_f32 v[170:171], v[244:245], v[64:65], v[252:253] op_sel_hi:[0,1,0]
	v_pk_fma_f32 v[164:165], v[242:243], v[68:69], v[164:165] op_sel_hi:[0,1,1]
	v_pk_fma_f32 v[168:169], v[248:249], v[64:65], v[168:169] op_sel_hi:[0,1,1]
	v_pk_fma_f32 v[166:167], v[242:243], v[70:71], v[166:167] op_sel_hi:[0,1,1]
	v_pk_fma_f32 v[170:171], v[248:249], v[66:67], v[170:171] op_sel_hi:[0,1,1]
	v_fmac_f32_e32 v164, v240, v141
	v_fmac_f32_e32 v168, v246, v143
	v_fmac_f32_e32 v165, v240, v68
	v_fmac_f32_e32 v169, v246, v64
	v_fmac_f32_e32 v166, v240, v69
	v_fmac_f32_e32 v170, v246, v65
	v_fmac_f32_e32 v167, v240, v70
	v_fmac_f32_e32 v171, v246, v66
	v_exp_f32_e32 v144, v164
	v_exp_f32_e32 v145, v165
	v_exp_f32_e32 v146, v166
	v_exp_f32_e32 v147, v167
	v_pk_mul_f32 v[164:165], v[164:165], v[168:169]
	v_pk_mul_f32 v[166:167], v[166:167], v[170:171]
	v_pk_add_f32 v[144:145], v[144:145], v[162:163]
	v_pk_add_f32 v[146:147], v[146:147], v[162:163]
	v_rcp_f32_e32 v144, v144
	v_rcp_f32_e32 v145, v145
	v_rcp_f32_e32 v146, v146
	v_rcp_f32_e32 v147, v147
	s_waitcnt lgkmcnt(8)
	v_cndmask_b32_e64 v140, v224, v216, s[8:9]
	v_cndmask_b32_e64 v141, v225, v217, s[8:9]
	v_cndmask_b32_e64 v142, v226, v218, s[8:9]
	v_cndmask_b32_e64 v143, v227, v219, s[8:9]
	v_pk_fma_f32 v[182:183], v[238:239], v[140:141], v[250:251] op_sel:[1,0,1] op_sel_hi:[1,1,1]
	v_pk_fma_f32 v[186:187], v[244:245], v[142:143], v[252:253] op_sel:[1,0,1] op_sel_hi:[1,1,1]
	v_pk_fma_f32 v[184:185], v[238:239], v[76:77], v[250:251] op_sel:[1,0,1] op_sel_hi:[1,1,1]
	v_pk_fma_f32 v[188:189], v[244:245], v[72:73], v[252:253] op_sel:[1,0,1] op_sel_hi:[1,1,1]
	v_pk_fma_f32 v[182:183], v[242:243], v[76:77], v[182:183] op_sel:[1,0,0] op_sel_hi:[1,1,1]
	v_pk_fma_f32 v[186:187], v[248:249], v[72:73], v[186:187] op_sel:[1,0,0] op_sel_hi:[1,1,1]
	v_pk_fma_f32 v[184:185], v[242:243], v[78:79], v[184:185] op_sel:[1,0,0] op_sel_hi:[1,1,1]
	v_pk_fma_f32 v[188:189], v[248:249], v[74:75], v[188:189] op_sel:[1,0,0] op_sel_hi:[1,1,1]
	v_fmac_f32_e32 v182, v241, v141
	v_fmac_f32_e32 v186, v247, v143
	v_fmac_f32_e32 v183, v241, v76
	v_fmac_f32_e32 v187, v247, v72
	v_fmac_f32_e32 v184, v241, v77
	v_fmac_f32_e32 v188, v247, v73
	v_fmac_f32_e32 v185, v241, v78
	v_fmac_f32_e32 v189, v247, v74
	v_exp_f32_e32 v148, v182
	v_exp_f32_e32 v149, v183
	v_exp_f32_e32 v150, v184
	v_exp_f32_e32 v151, v185
	v_pk_mul_f32 v[182:183], v[182:183], v[186:187]
	v_pk_mul_f32 v[184:185], v[184:185], v[188:189]
	v_pk_add_f32 v[148:149], v[148:149], v[162:163]
	v_pk_add_f32 v[150:151], v[150:151], v[162:163]
	v_rcp_f32_e32 v148, v148
	v_rcp_f32_e32 v149, v149
	v_rcp_f32_e32 v150, v150
	v_rcp_f32_e32 v151, v151
	v_pk_mul_f32 v[164:165], v[164:165], v[144:145]
	v_pk_mul_f32 v[166:167], v[166:167], v[146:147]
	v_pk_mul_f32 v[182:183], v[182:183], v[148:149]
	v_pk_mul_f32 v[184:185], v[184:185], v[150:151]
	v_cvt_pk_bf16_f32 v152, v164, v182
	v_cvt_pk_bf16_f32 v153, v165, v183
	v_cvt_pk_bf16_f32 v154, v166, v184
	v_cvt_pk_bf16_f32 v155, v167, v185
	global_store_dword v157, v152, s[76:77]
	s_add_u32 s76, s76, 0x1600
	s_addc_u32 s77, s77, 0
	global_store_dword v157, v153, s[76:77]
	s_add_u32 s76, s76, 0x1600
	s_addc_u32 s77, s77, 0
	global_store_dword v157, v154, s[76:77]
	s_add_u32 s76, s76, 0x1600
	s_addc_u32 s77, s77, 0
	global_store_dword v157, v155, s[76:77]
	s_add_u32 s76, s76, 0x69e00
	s_addc_u32 s77, s77, 0
	ds_bpermute_b32 v204, v158, v46
	ds_bpermute_b32 v205, v158, v47
	ds_bpermute_b32 v206, v158, v42
	ds_bpermute_b32 v207, v158, v43
	ds_bpermute_b32 v208, v158, v38
	ds_bpermute_b32 v209, v158, v39
	s_waitcnt lgkmcnt(13)
;     __device__ __forceinline__ void operator()(const f32x4 (&acc)[2][2][4][2], const Unit& u, int wr, int wc, int fr, int fq) const {
;     ...
;                 for (int n = 0; n < 2; ++n) {
;                     const f32x4 Xa = acc[ai][0][m][n], Xb = acc[ai][1][m][n];
;                     float da2, da3, db2, db3;
;                     if (m > 0) { const bool t = (fq == 3); da2 = t ? acc[ai][0][m > 0 ? m - 1 : 0][n][2] : Xa[2]; da3 = t ? acc[ai][0][m > 0 ? m - 1 : 0][n][3] : Xa[3];
;                                  db2 = t ? acc[ai][1][m > 0 ? m - 1 : 0][n][2] : Xb[2]; db3 = t ? acc[ai][1][m > 0 ? m - 1 : 0][n][3] : Xb[3]; }
;                     else { da2 = Xa[2]; da3 = Xa[3]; db2 = Xb[2]; db3 = Xb[3]; }
;                     float Ha2 = __builtin_bit_cast(float, __builtin_amdgcn_ds_bpermute(src, __builtin_bit_cast(int, da2)));
;                     float Ha3 = __builtin_bit_cast(float, __builtin_amdgcn_ds_bpermute(src, __builtin_bit_cast(int, da3)));
;                     float Hb2 = __builtin_bit_cast(float, __builtin_amdgcn_ds_bpermute(src, __builtin_bit_cast(int, db2)));
;                     float Hb3 = __builtin_bit_cast(float, __builtin_amdgcn_ds_bpermute(src, __builtin_bit_cast(int, db3)));
;                     if (m == 0) {
;                         float h2a = 0.f, h3a = 0.f, h2b = 0.f, h3b = 0.f;
;                         if (blk > 0) { const PG8_LAS float* hp = halo + ((((blk - 1) * 4 + wc) * 2 + 0) * 2 + n) * 32 + fr; h2a = hp[0]; h3a = hp[16]; h2b = hp[64]; h3b = hp[80]; }
;                         if (fq == 0) { Ha2 = h2a; Ha3 = h3a; Hb2 = h2b; Hb3 = h3b; }
;                     }
;                     const f32x2_t W0 = {wa[n][0], wb[n][0]}, W1 = {wa[n][1], wb[n][1]}, W2 = {wa[n][2], wb[n][2]}, B2 = {ba[n], bb[n]};
;                     const f32x2_t H2 = {Ha2, Hb2}, H3 = {Ha3, Hb3}, X0 = {Xa[0], Xb[0]}, X1 = {Xa[1], Xb[1]}, X2 = {Xa[2], Xb[2]}, X3 = {Xa[3], Xb[3]};
;                     const f32x2_t y0 = B2 + W0 * H2 + W1 * H3 + W2 * X0, y1 = B2 + W0 * H3 + W1 * X0 + W2 * X1, y2 = B2 + W0 * X0 + W1 * X1 + W2 * X2, y3 = B2 + W0 * X1 + W1 * X2 + W2 * X3;
;                     const float ya0 = y0[0], yb0 = y0[1], ya1 = y1[0], yb1 = y1[1], ya2 = y2[0], yb2 = y2[1], ya3 = y3[0], yb3 = y3[1];
;                     o[n][0] = silu_f(ya0) * yb0; o[n][1] = silu_f(ya1) * yb1; o[n][2] = silu_f(ya2) * yb2; o[n][3] = silu_f(ya3) * yb3;
	ds_bpermute_b32 v210, v158, v34
	s_waitcnt lgkmcnt(13)
	ds_bpermute_b32 v211, v158, v35
	s_waitcnt lgkmcnt(12)
	v_cndmask_b32_e64 v140, v196, v228, s[8:9]
	v_cndmask_b32_e64 v141, v197, v229, s[8:9]
	v_cndmask_b32_e64 v142, v198, v230, s[8:9]
	v_cndmask_b32_e64 v143, v199, v231, s[8:9]
	v_pk_fma_f32 v[164:165], v[238:239], v[140:141], v[250:251] op_sel_hi:[0,1,0]
	v_pk_fma_f32 v[168:169], v[244:245], v[142:143], v[252:253] op_sel_hi:[0,1,0]
	v_pk_fma_f32 v[166:167], v[238:239], v[60:61], v[250:251] op_sel_hi:[0,1,0]
	v_pk_fma_f32 v[170:171], v[244:245], v[56:57], v[252:253] op_sel_hi:[0,1,0]
	v_pk_fma_f32 v[164:165], v[242:243], v[60:61], v[164:165] op_sel_hi:[0,1,1]
	v_pk_fma_f32 v[168:169], v[248:249], v[56:57], v[168:169] op_sel_hi:[0,1,1]
	v_pk_fma_f32 v[166:167], v[242:243], v[62:63], v[166:167] op_sel_hi:[0,1,1]
	v_pk_fma_f32 v[170:171], v[248:249], v[58:59], v[170:171] op_sel_hi:[0,1,1]
	v_fmac_f32_e32 v164, v240, v141
	v_fmac_f32_e32 v168, v246, v143
	v_fmac_f32_e32 v165, v240, v60
	v_fmac_f32_e32 v169, v246, v56
	v_fmac_f32_e32 v166, v240, v61
	v_fmac_f32_e32 v170, v246, v57
	v_fmac_f32_e32 v167, v240, v62
	v_fmac_f32_e32 v171, v246, v58
	v_exp_f32_e32 v144, v164
	v_exp_f32_e32 v145, v165
	v_exp_f32_e32 v146, v166
	v_exp_f32_e32 v147, v167
	v_pk_mul_f32 v[164:165], v[164:165], v[168:169]
	v_pk_mul_f32 v[166:167], v[166:167], v[170:171]
	v_pk_add_f32 v[144:145], v[144:145], v[162:163]
	v_pk_add_f32 v[146:147], v[146:147], v[162:163]
	v_rcp_f32_e32 v144, v144
	v_rcp_f32_e32 v145, v145
	v_rcp_f32_e32 v146, v146
	v_rcp_f32_e32 v147, v147
	s_waitcnt lgkmcnt(8)
	v_cndmask_b32_e64 v140, v200, v232, s[8:9]
	v_cndmask_b32_e64 v141, v201, v233, s[8:9]
	v_cndmask_b32_e64 v142, v202, v234, s[8:9]
	v_cndmask_b32_e64 v143, v203, v235, s[8:9]
	v_pk_fma_f32 v[182:183], v[238:239], v[140:141], v[250:251] op_sel:[1,0,1] op_sel_hi:[1,1,1]
	v_pk_fma_f32 v[186:187], v[244:245], v[142:143], v[252:253] op_sel:[1,0,1] op_sel_hi:[1,1,1]
	v_pk_fma_f32 v[184:185], v[238:239], v[52:53], v[250:251] op_sel:[1,0,1] op_sel_hi:[1,1,1]
	v_pk_fma_f32 v[188:189], v[244:245], v[48:49], v[252:253] op_sel:[1,0,1] op_sel_hi:[1,1,1]
	v_pk_fma_f32 v[182:183], v[242:243], v[52:53], v[182:183] op_sel:[1,0,0] op_sel_hi:[1,1,1]
	v_pk_fma_f32 v[186:187], v[248:249], v[48:49], v[186:187] op_sel:[1,0,0] op_sel_hi:[1,1,1]
	v_pk_fma_f32 v[184:185], v[242:243], v[54:55], v[184:185] op_sel:[1,0,0] op_sel_hi:[1,1,1]
	v_pk_fma_f32 v[188:189], v[248:249], v[50:51], v[188:189] op_sel:[1,0,0] op_sel_hi:[1,1,1]
	v_fmac_f32_e32 v182, v241, v141
	v_fmac_f32_e32 v186, v247, v143
	v_fmac_f32_e32 v183, v241, v52
	v_fmac_f32_e32 v187, v247, v48
	v_fmac_f32_e32 v184, v241, v53
	v_fmac_f32_e32 v188, v247, v49
	v_fmac_f32_e32 v185, v241, v54
	v_fmac_f32_e32 v189, v247, v50
	v_exp_f32_e32 v148, v182
	v_exp_f32_e32 v149, v183
	v_exp_f32_e32 v150, v184
	v_exp_f32_e32 v151, v185
	v_pk_mul_f32 v[182:183], v[182:183], v[186:187]
	v_pk_mul_f32 v[184:185], v[184:185], v[188:189]
	v_pk_add_f32 v[148:149], v[148:149], v[162:163]
	v_pk_add_f32 v[150:151], v[150:151], v[162:163]
	v_rcp_f32_e32 v148, v148
	v_rcp_f32_e32 v149, v149
	v_rcp_f32_e32 v150, v150
	v_rcp_f32_e32 v151, v151
	v_pk_mul_f32 v[164:165], v[164:165], v[144:145]
	v_pk_mul_f32 v[166:167], v[166:167], v[146:147]
	v_pk_mul_f32 v[182:183], v[182:183], v[148:149]
	v_pk_mul_f32 v[184:185], v[184:185], v[150:151]
	v_cvt_pk_bf16_f32 v152, v164, v182
	v_cvt_pk_bf16_f32 v153, v165, v183
	v_cvt_pk_bf16_f32 v154, v166, v184
	v_cvt_pk_bf16_f32 v155, v167, v185
	global_store_dword v157, v152, s[76:77]
	s_add_u32 s76, s76, 0x1600
	s_addc_u32 s77, s77, 0
	global_store_dword v157, v153, s[76:77]
	s_add_u32 s76, s76, 0x1600
	s_addc_u32 s77, s77, 0
	global_store_dword v157, v154, s[76:77]
	s_add_u32 s76, s76, 0x1600
	s_addc_u32 s77, s77, 0
	global_store_dword v157, v155, s[76:77]
	s_add_u32 s76, s76, 0x11e00
	s_addc_u32 s77, s77, 0
	ds_bpermute_b32 v212, v158, v30
	ds_bpermute_b32 v213, v158, v31
	ds_bpermute_b32 v214, v158, v26
	ds_bpermute_b32 v215, v158, v27
	ds_bpermute_b32 v216, v158, v22
	ds_bpermute_b32 v217, v158, v23
	s_waitcnt lgkmcnt(13)
	ds_bpermute_b32 v218, v158, v18
	s_waitcnt lgkmcnt(13)
	ds_bpermute_b32 v219, v158, v19
	s_waitcnt lgkmcnt(12)
	v_cndmask_b32_e64 v140, v204, v196, s[8:9]
	v_cndmask_b32_e64 v141, v205, v197, s[8:9]
	v_cndmask_b32_e64 v142, v206, v198, s[8:9]
	v_cndmask_b32_e64 v143, v207, v199, s[8:9]
	v_pk_fma_f32 v[164:165], v[238:239], v[140:141], v[250:251] op_sel_hi:[0,1,0]
	v_pk_fma_f32 v[168:169], v[244:245], v[142:143], v[252:253] op_sel_hi:[0,1,0]
	v_pk_fma_f32 v[166:167], v[238:239], v[44:45], v[250:251] op_sel_hi:[0,1,0]
	v_pk_fma_f32 v[170:171], v[244:245], v[40:41], v[252:253] op_sel_hi:[0,1,0]
	v_pk_fma_f32 v[164:165], v[242:243], v[44:45], v[164:165] op_sel_hi:[0,1,1]
	v_pk_fma_f32 v[168:169], v[248:249], v[40:41], v[168:169] op_sel_hi:[0,1,1]
	v_pk_fma_f32 v[166:167], v[242:243], v[46:47], v[166:167] op_sel_hi:[0,1,1]
	v_pk_fma_f32 v[170:171], v[248:249], v[42:43], v[170:171] op_sel_hi:[0,1,1]
	v_fmac_f32_e32 v164, v240, v141
	v_fmac_f32_e32 v168, v246, v143
	v_fmac_f32_e32 v165, v240, v44
	v_fmac_f32_e32 v169, v246, v40
	v_fmac_f32_e32 v166, v240, v45
	v_fmac_f32_e32 v170, v246, v41
	v_fmac_f32_e32 v167, v240, v46
	v_fmac_f32_e32 v171, v246, v42
	v_exp_f32_e32 v144, v164
	v_exp_f32_e32 v145, v165
	v_exp_f32_e32 v146, v166
	v_exp_f32_e32 v147, v167
	v_pk_mul_f32 v[164:165], v[164:165], v[168:169]
	v_pk_mul_f32 v[166:167], v[166:167], v[170:171]
	v_pk_add_f32 v[144:145], v[144:145], v[162:163]
	v_pk_add_f32 v[146:147], v[146:147], v[162:163]
	v_rcp_f32_e32 v144, v144
	v_rcp_f32_e32 v145, v145
	v_rcp_f32_e32 v146, v146
	v_rcp_f32_e32 v147, v147
	s_waitcnt lgkmcnt(8)
;     __device__ __forceinline__ void operator()(const f32x4 (&acc)[2][2][4][2], const Unit& u, int wr, int wc, int fr, int fq) const {
;     ...
;                 for (int n = 0; n < 2; ++n) {
;                     const f32x4 Xa = acc[ai][0][m][n], Xb = acc[ai][1][m][n];
;                     float da2, da3, db2, db3;
;                     if (m > 0) { const bool t = (fq == 3); da2 = t ? acc[ai][0][m > 0 ? m - 1 : 0][n][2] : Xa[2]; da3 = t ? acc[ai][0][m > 0 ? m - 1 : 0][n][3] : Xa[3];
;                                  db2 = t ? acc[ai][1][m > 0 ? m - 1 : 0][n][2] : Xb[2]; db3 = t ? acc[ai][1][m > 0 ? m - 1 : 0][n][3] : Xb[3]; }
;                     else { da2 = Xa[2]; da3 = Xa[3]; db2 = Xb[2]; db3 = Xb[3]; }
;                     float Ha2 = __builtin_bit_cast(float, __builtin_amdgcn_ds_bpermute(src, __builtin_bit_cast(int, da2)));
;                     float Ha3 = __builtin_bit_cast(float, __builtin_amdgcn_ds_bpermute(src, __builtin_bit_cast(int, da3)));
;                     float Hb2 = __builtin_bit_cast(float, __builtin_amdgcn_ds_bpermute(src, __builtin_bit_cast(int, db2)));
;                     float Hb3 = __builtin_bit_cast(float, __builtin_amdgcn_ds_bpermute(src, __builtin_bit_cast(int, db3)));
;                     if (m == 0) {
;                         float h2a = 0.f, h3a = 0.f, h2b = 0.f, h3b = 0.f;
;                         if (blk > 0) { const PG8_LAS float* hp = halo + ((((blk - 1) * 4 + wc) * 2 + 0) * 2 + n) * 32 + fr; h2a = hp[0]; h3a = hp[16]; h2b = hp[64]; h3b = hp[80]; }
;                         if (fq == 0) { Ha2 = h2a; Ha3 = h3a; Hb2 = h2b; Hb3 = h3b; }
;                     }
;                     const f32x2_t W0 = {wa[n][0], wb[n][0]}, W1 = {wa[n][1], wb[n][1]}, W2 = {wa[n][2], wb[n][2]}, B2 = {ba[n], bb[n]};
;                     const f32x2_t H2 = {Ha2, Hb2}, H3 = {Ha3, Hb3}, X0 = {Xa[0], Xb[0]}, X1 = {Xa[1], Xb[1]}, X2 = {Xa[2], Xb[2]}, X3 = {Xa[3], Xb[3]};
;                     const f32x2_t y0 = B2 + W0 * H2 + W1 * H3 + W2 * X0, y1 = B2 + W0 * H3 + W1 * X0 + W2 * X1, y2 = B2 + W0 * X0 + W1 * X1 + W2 * X2, y3 = B2 + W0 * X1 + W1 * X2 + W2 * X3;
;                     const float ya0 = y0[0], yb0 = y0[1], ya1 = y1[0], yb1 = y1[1], ya2 = y2[0], yb2 = y2[1], ya3 = y3[0], yb3 = y3[1];
;                     o[n][0] = silu_f(ya0) * yb0; o[n][1] = silu_f(ya1) * yb1; o[n][2] = silu_f(ya2) * yb2; o[n][3] = silu_f(ya3) * yb3;
	v_cndmask_b32_e64 v140, v208, v200, s[8:9]
	v_cndmask_b32_e64 v141, v209, v201, s[8:9]
	v_cndmask_b32_e64 v142, v210, v202, s[8:9]
	v_cndmask_b32_e64 v143, v211, v203, s[8:9]
	v_pk_fma_f32 v[182:183], v[238:239], v[140:141], v[250:251] op_sel:[1,0,1] op_sel_hi:[1,1,1]
	v_pk_fma_f32 v[186:187], v[244:245], v[142:143], v[252:253] op_sel:[1,0,1] op_sel_hi:[1,1,1]
	v_pk_fma_f32 v[184:185], v[238:239], v[36:37], v[250:251] op_sel:[1,0,1] op_sel_hi:[1,1,1]
	v_pk_fma_f32 v[188:189], v[244:245], v[32:33], v[252:253] op_sel:[1,0,1] op_sel_hi:[1,1,1]
	v_pk_fma_f32 v[182:183], v[242:243], v[36:37], v[182:183] op_sel:[1,0,0] op_sel_hi:[1,1,1]
	v_pk_fma_f32 v[186:187], v[248:249], v[32:33], v[186:187] op_sel:[1,0,0] op_sel_hi:[1,1,1]
	v_pk_fma_f32 v[184:185], v[242:243], v[38:39], v[184:185] op_sel:[1,0,0] op_sel_hi:[1,1,1]
	v_pk_fma_f32 v[188:189], v[248:249], v[34:35], v[188:189] op_sel:[1,0,0] op_sel_hi:[1,1,1]
	v_fmac_f32_e32 v182, v241, v141
	v_fmac_f32_e32 v186, v247, v143
	v_fmac_f32_e32 v183, v241, v36
	v_fmac_f32_e32 v187, v247, v32
	v_fmac_f32_e32 v184, v241, v37
	v_fmac_f32_e32 v188, v247, v33
	v_fmac_f32_e32 v185, v241, v38
	v_fmac_f32_e32 v189, v247, v34
	v_exp_f32_e32 v148, v182
	v_exp_f32_e32 v149, v183
	v_exp_f32_e32 v150, v184
	v_exp_f32_e32 v151, v185
	v_pk_mul_f32 v[182:183], v[182:183], v[186:187]
	v_pk_mul_f32 v[184:185], v[184:185], v[188:189]
	v_pk_add_f32 v[148:149], v[148:149], v[162:163]
	v_pk_add_f32 v[150:151], v[150:151], v[162:163]
	v_rcp_f32_e32 v148, v148
	v_rcp_f32_e32 v149, v149
	v_rcp_f32_e32 v150, v150
	v_rcp_f32_e32 v151, v151
	v_pk_mul_f32 v[164:165], v[164:165], v[144:145]
	v_pk_mul_f32 v[166:167], v[166:167], v[146:147]
	v_pk_mul_f32 v[182:183], v[182:183], v[148:149]
	v_pk_mul_f32 v[184:185], v[184:185], v[150:151]
	v_cvt_pk_bf16_f32 v152, v164, v182
	v_cvt_pk_bf16_f32 v153, v165, v183
	v_cvt_pk_bf16_f32 v154, v166, v184
	v_cvt_pk_bf16_f32 v155, v167, v185
	global_store_dword v157, v152, s[76:77]
	s_add_u32 s76, s76, 0x1600
	s_addc_u32 s77, s77, 0
	global_store_dword v157, v153, s[76:77]
	s_add_u32 s76, s76, 0x1600
	s_addc_u32 s77, s77, 0
	global_store_dword v157, v154, s[76:77]
	s_add_u32 s76, s76, 0x1600
	s_addc_u32 s77, s77, 0
	global_store_dword v157, v155, s[76:77]
	s_add_u32 s76, s76, 0x11e00
	s_addc_u32 s77, s77, 0
	ds_bpermute_b32 v220, v158, v2
	ds_bpermute_b32 v221, v158, v3
	ds_bpermute_b32 v222, v158, v6
	ds_bpermute_b32 v223, v158, v7
	ds_bpermute_b32 v224, v158, v14
	ds_bpermute_b32 v225, v158, v15
	s_waitcnt lgkmcnt(13)
	ds_bpermute_b32 v226, v158, v10
	s_waitcnt lgkmcnt(13)
	ds_bpermute_b32 v227, v158, v11
	s_waitcnt lgkmcnt(12)
	v_cndmask_b32_e64 v140, v212, v204, s[8:9]
	v_cndmask_b32_e64 v141, v213, v205, s[8:9]
	v_cndmask_b32_e64 v142, v214, v206, s[8:9]
	v_cndmask_b32_e64 v143, v215, v207, s[8:9]
	v_pk_fma_f32 v[164:165], v[238:239], v[140:141], v[250:251] op_sel_hi:[0,1,0]
	v_pk_fma_f32 v[168:169], v[244:245], v[142:143], v[252:253] op_sel_hi:[0,1,0]
	v_pk_fma_f32 v[166:167], v[238:239], v[28:29], v[250:251] op_sel_hi:[0,1,0]
	v_pk_fma_f32 v[170:171], v[244:245], v[24:25], v[252:253] op_sel_hi:[0,1,0]
	v_pk_fma_f32 v[164:165], v[242:243], v[28:29], v[164:165] op_sel_hi:[0,1,1]
	v_pk_fma_f32 v[168:169], v[248:249], v[24:25], v[168:169] op_sel_hi:[0,1,1]
	v_pk_fma_f32 v[166:167], v[242:243], v[30:31], v[166:167] op_sel_hi:[0,1,1]
	v_pk_fma_f32 v[170:171], v[248:249], v[26:27], v[170:171] op_sel_hi:[0,1,1]
	v_fmac_f32_e32 v164, v240, v141
	v_fmac_f32_e32 v168, v246, v143
	v_fmac_f32_e32 v165, v240, v28
	v_fmac_f32_e32 v169, v246, v24
	v_fmac_f32_e32 v166, v240, v29
	v_fmac_f32_e32 v170, v246, v25
	v_fmac_f32_e32 v167, v240, v30
	v_fmac_f32_e32 v171, v246, v26
	v_exp_f32_e32 v144, v164
	v_exp_f32_e32 v145, v165
	v_exp_f32_e32 v146, v166
	v_exp_f32_e32 v147, v167
	v_pk_mul_f32 v[164:165], v[164:165], v[168:169]
	v_pk_mul_f32 v[166:167], v[166:167], v[170:171]
	v_pk_add_f32 v[144:145], v[144:145], v[162:163]
	v_pk_add_f32 v[146:147], v[146:147], v[162:163]
	v_rcp_f32_e32 v144, v144
	v_rcp_f32_e32 v145, v145
	v_rcp_f32_e32 v146, v146
	v_rcp_f32_e32 v147, v147
	s_waitcnt lgkmcnt(8)
;     __device__ __forceinline__ void operator()(const f32x4 (&acc)[2][2][4][2], const Unit& u, int wr, int wc, int fr, int fq) const {
;     ...
;                 for (int n = 0; n < 2; ++n) {
;                     const f32x4 Xa = acc[ai][0][m][n], Xb = acc[ai][1][m][n];
;                     float da2, da3, db2, db3;
;                     if (m > 0) { const bool t = (fq == 3); da2 = t ? acc[ai][0][m > 0 ? m - 1 : 0][n][2] : Xa[2]; da3 = t ? acc[ai][0][m > 0 ? m - 1 : 0][n][3] : Xa[3];
;                                  db2 = t ? acc[ai][1][m > 0 ? m - 1 : 0][n][2] : Xb[2]; db3 = t ? acc[ai][1][m > 0 ? m - 1 : 0][n][3] : Xb[3]; }
;                     else { da2 = Xa[2]; da3 = Xa[3]; db2 = Xb[2]; db3 = Xb[3]; }
;                     float Ha2 = __builtin_bit_cast(float, __builtin_amdgcn_ds_bpermute(src, __builtin_bit_cast(int, da2)));
;                     float Ha3 = __builtin_bit_cast(float, __builtin_amdgcn_ds_bpermute(src, __builtin_bit_cast(int, da3)));
;                     float Hb2 = __builtin_bit_cast(float, __builtin_amdgcn_ds_bpermute(src, __builtin_bit_cast(int, db2)));
;                     float Hb3 = __builtin_bit_cast(float, __builtin_amdgcn_ds_bpermute(src, __builtin_bit_cast(int, db3)));
;                     if (m == 0) {
;                         float h2a = 0.f, h3a = 0.f, h2b = 0.f, h3b = 0.f;
;                         if (blk > 0) { const PG8_LAS float* hp = halo + ((((blk - 1) * 4 + wc) * 2 + 0) * 2 + n) * 32 + fr; h2a = hp[0]; h3a = hp[16]; h2b = hp[64]; h3b = hp[80]; }
;                         if (fq == 0) { Ha2 = h2a; Ha3 = h3a; Hb2 = h2b; Hb3 = h3b; }
;                     }
;                     const f32x2_t W0 = {wa[n][0], wb[n][0]}, W1 = {wa[n][1], wb[n][1]}, W2 = {wa[n][2], wb[n][2]}, B2 = {ba[n], bb[n]};
;                     const f32x2_t H2 = {Ha2, Hb2}, H3 = {Ha3, Hb3}, X0 = {Xa[0], Xb[0]}, X1 = {Xa[1], Xb[1]}, X2 = {Xa[2], Xb[2]}, X3 = {Xa[3], Xb[3]};
;                     const f32x2_t y0 = B2 + W0 * H2 + W1 * H3 + W2 * X0, y1 = B2 + W0 * H3 + W1 * X0 + W2 * X1, y2 = B2 + W0 * X0 + W1 * X1 + W2 * X2, y3 = B2 + W0 * X1 + W1 * X2 + W2 * X3;
;                     const float ya0 = y0[0], yb0 = y0[1], ya1 = y1[0], yb1 = y1[1], ya2 = y2[0], yb2 = y2[1], ya3 = y3[0], yb3 = y3[1];
;                     o[n][0] = silu_f(ya0) * yb0; o[n][1] = silu_f(ya1) * yb1; o[n][2] = silu_f(ya2) * yb2; o[n][3] = silu_f(ya3) * yb3;
	v_cndmask_b32_e64 v140, v216, v208, s[8:9]
	v_cndmask_b32_e64 v141, v217, v209, s[8:9]
	v_cndmask_b32_e64 v142, v218, v210, s[8:9]
	v_cndmask_b32_e64 v143, v219, v211, s[8:9]
	v_pk_fma_f32 v[182:183], v[238:239], v[140:141], v[250:251] op_sel:[1,0,1] op_sel_hi:[1,1,1]
	v_pk_fma_f32 v[186:187], v[244:245], v[142:143], v[252:253] op_sel:[1,0,1] op_sel_hi:[1,1,1]
	v_pk_fma_f32 v[184:185], v[238:239], v[20:21], v[250:251] op_sel:[1,0,1] op_sel_hi:[1,1,1]
	v_pk_fma_f32 v[188:189], v[244:245], v[16:17], v[252:253] op_sel:[1,0,1] op_sel_hi:[1,1,1]
	v_pk_fma_f32 v[182:183], v[242:243], v[20:21], v[182:183] op_sel:[1,0,0] op_sel_hi:[1,1,1]
	v_pk_fma_f32 v[186:187], v[248:249], v[16:17], v[186:187] op_sel:[1,0,0] op_sel_hi:[1,1,1]
	v_pk_fma_f32 v[184:185], v[242:243], v[22:23], v[184:185] op_sel:[1,0,0] op_sel_hi:[1,1,1]
	v_pk_fma_f32 v[188:189], v[248:249], v[18:19], v[188:189] op_sel:[1,0,0] op_sel_hi:[1,1,1]
	v_fmac_f32_e32 v182, v241, v141
	v_fmac_f32_e32 v186, v247, v143
	v_fmac_f32_e32 v183, v241, v20
	v_fmac_f32_e32 v187, v247, v16
	v_fmac_f32_e32 v184, v241, v21
	v_fmac_f32_e32 v188, v247, v17
	v_fmac_f32_e32 v185, v241, v22
	v_fmac_f32_e32 v189, v247, v18
	v_exp_f32_e32 v148, v182
	v_exp_f32_e32 v149, v183
	v_exp_f32_e32 v150, v184
	v_exp_f32_e32 v151, v185
	v_pk_mul_f32 v[182:183], v[182:183], v[186:187]
	v_pk_mul_f32 v[184:185], v[184:185], v[188:189]
	v_pk_add_f32 v[148:149], v[148:149], v[162:163]
	v_pk_add_f32 v[150:151], v[150:151], v[162:163]
	v_rcp_f32_e32 v148, v148
	v_rcp_f32_e32 v149, v149
	v_rcp_f32_e32 v150, v150
	v_rcp_f32_e32 v151, v151
	v_pk_mul_f32 v[164:165], v[164:165], v[144:145]
	v_pk_mul_f32 v[166:167], v[166:167], v[146:147]
	v_pk_mul_f32 v[182:183], v[182:183], v[148:149]
	v_pk_mul_f32 v[184:185], v[184:185], v[150:151]
	v_cvt_pk_bf16_f32 v152, v164, v182
	v_cvt_pk_bf16_f32 v153, v165, v183
	v_cvt_pk_bf16_f32 v154, v166, v184
	v_cvt_pk_bf16_f32 v155, v167, v185
	global_store_dword v157, v152, s[76:77]
	s_add_u32 s76, s76, 0x1600
	s_addc_u32 s77, s77, 0
	global_store_dword v157, v153, s[76:77]
	s_add_u32 s76, s76, 0x1600
	s_addc_u32 s77, s77, 0
	global_store_dword v157, v154, s[76:77]
	s_add_u32 s76, s76, 0x1600
	s_addc_u32 s77, s77, 0
	global_store_dword v157, v155, s[76:77]
	s_add_u32 s76, s76, 0x11e00
	s_addc_u32 s77, s77, 0
	s_waitcnt lgkmcnt(4)
	v_cndmask_b32_e64 v140, v220, v212, s[8:9]
	v_cndmask_b32_e64 v141, v221, v213, s[8:9]
	v_cndmask_b32_e64 v142, v222, v214, s[8:9]
	v_cndmask_b32_e64 v143, v223, v215, s[8:9]
	v_pk_fma_f32 v[164:165], v[238:239], v[140:141], v[250:251] op_sel_hi:[0,1,0]
	v_pk_fma_f32 v[168:169], v[244:245], v[142:143], v[252:253] op_sel_hi:[0,1,0]
	v_pk_fma_f32 v[166:167], v[238:239], v[0:1], v[250:251] op_sel_hi:[0,1,0]
	v_pk_fma_f32 v[170:171], v[244:245], v[4:5], v[252:253] op_sel_hi:[0,1,0]
	v_pk_fma_f32 v[164:165], v[242:243], v[0:1], v[164:165] op_sel_hi:[0,1,1]
	v_pk_fma_f32 v[168:169], v[248:249], v[4:5], v[168:169] op_sel_hi:[0,1,1]
	v_pk_fma_f32 v[166:167], v[242:243], v[2:3], v[166:167] op_sel_hi:[0,1,1]
	v_pk_fma_f32 v[170:171], v[248:249], v[6:7], v[170:171] op_sel_hi:[0,1,1]
	v_fmac_f32_e32 v164, v240, v141
	v_fmac_f32_e32 v168, v246, v143
	v_fmac_f32_e32 v165, v240, v0
	v_fmac_f32_e32 v169, v246, v4
	v_fmac_f32_e32 v166, v240, v1
	v_fmac_f32_e32 v170, v246, v5
	v_fmac_f32_e32 v167, v240, v2
	v_fmac_f32_e32 v171, v246, v6
	v_exp_f32_e32 v144, v164
	v_exp_f32_e32 v145, v165
	v_exp_f32_e32 v146, v166
	v_exp_f32_e32 v147, v167
	v_pk_mul_f32 v[164:165], v[164:165], v[168:169]
	v_pk_mul_f32 v[166:167], v[166:167], v[170:171]
	v_pk_add_f32 v[144:145], v[144:145], v[162:163]
	v_pk_add_f32 v[146:147], v[146:147], v[162:163]
	v_rcp_f32_e32 v144, v144
	v_rcp_f32_e32 v145, v145
	v_rcp_f32_e32 v146, v146
	v_rcp_f32_e32 v147, v147
	s_waitcnt lgkmcnt(0)
	v_cndmask_b32_e64 v140, v224, v216, s[8:9]
	v_cndmask_b32_e64 v141, v225, v217, s[8:9]
	v_cndmask_b32_e64 v142, v226, v218, s[8:9]
	v_cndmask_b32_e64 v143, v227, v219, s[8:9]
	v_pk_fma_f32 v[182:183], v[238:239], v[140:141], v[250:251] op_sel:[1,0,1] op_sel_hi:[1,1,1]
	v_pk_fma_f32 v[186:187], v[244:245], v[142:143], v[252:253] op_sel:[1,0,1] op_sel_hi:[1,1,1]
	v_pk_fma_f32 v[184:185], v[238:239], v[12:13], v[250:251] op_sel:[1,0,1] op_sel_hi:[1,1,1]
	v_pk_fma_f32 v[188:189], v[244:245], v[8:9], v[252:253] op_sel:[1,0,1] op_sel_hi:[1,1,1]
	v_pk_fma_f32 v[182:183], v[242:243], v[12:13], v[182:183] op_sel:[1,0,0] op_sel_hi:[1,1,1]
	v_pk_fma_f32 v[186:187], v[248:249], v[8:9], v[186:187] op_sel:[1,0,0] op_sel_hi:[1,1,1]
	v_pk_fma_f32 v[184:185], v[242:243], v[14:15], v[184:185] op_sel:[1,0,0] op_sel_hi:[1,1,1]
	v_pk_fma_f32 v[188:189], v[248:249], v[10:11], v[188:189] op_sel:[1,0,0] op_sel_hi:[1,1,1]
	v_fmac_f32_e32 v182, v241, v141
	v_fmac_f32_e32 v186, v247, v143
	v_fmac_f32_e32 v183, v241, v12
	v_fmac_f32_e32 v187, v247, v8
	v_fmac_f32_e32 v184, v241, v13
	v_fmac_f32_e32 v188, v247, v9
	v_fmac_f32_e32 v185, v241, v14
	v_fmac_f32_e32 v189, v247, v10
	v_exp_f32_e32 v148, v182
	v_exp_f32_e32 v149, v183
	v_exp_f32_e32 v150, v184
	v_exp_f32_e32 v151, v185
	v_pk_mul_f32 v[182:183], v[182:183], v[186:187]
	v_pk_mul_f32 v[184:185], v[184:185], v[188:189]
	v_pk_add_f32 v[148:149], v[148:149], v[162:163]
	v_pk_add_f32 v[150:151], v[150:151], v[162:163]
	v_rcp_f32_e32 v148, v148
	v_rcp_f32_e32 v149, v149
	v_rcp_f32_e32 v150, v150
	v_rcp_f32_e32 v151, v151
	v_pk_mul_f32 v[164:165], v[164:165], v[144:145]
	v_pk_mul_f32 v[166:167], v[166:167], v[146:147]
	v_pk_mul_f32 v[182:183], v[182:183], v[148:149]
	v_pk_mul_f32 v[184:185], v[184:185], v[150:151]
	v_cvt_pk_bf16_f32 v152, v164, v182
	v_cvt_pk_bf16_f32 v153, v165, v183
	v_cvt_pk_bf16_f32 v154, v166, v184
	v_cvt_pk_bf16_f32 v155, v167, v185
	global_store_dword v157, v152, s[76:77]
	s_add_u32 s76, s76, 0x1600
	s_addc_u32 s77, s77, 0
	global_store_dword v157, v153, s[76:77]
	s_add_u32 s76, s76, 0x1600
	s_addc_u32 s77, s77, 0
	global_store_dword v157, v154, s[76:77]
	s_add_u32 s76, s76, 0x1600
	s_addc_u32 s77, s77, 0
	global_store_dword v157, v155, s[76:77]
	s_cmp_eq_u32 s25, 0
	s_cbranch_scc1 .Lp8_noprio
	s_setprio 1
.Lp8_noprio:
	s_andn2_b64 vcc, exec, s[14:15]
	s_mov_b64 s[14:15], -1
	s_cbranch_vccnz .LBB0_882
	s_setprio 0
	s_andn2_b64 vcc, exec, s[38:39]
	s_cbranch_vccnz .LBB0_881
	s_barrier
	s_branch .LBB0_881
